# v59 + X-tile stores paired into ds_write2_b32 (per-4-row base computed on the fly)
# baseline (speedup 1.0000x reference)
; #define LAS __attribute__((address_space(3)))
; __device__ __forceinline__ unsigned pk2(float lo, float hi) { f32x2 v = {lo, hi}; nbf2 r = __builtin_convertvector(v, nbf2); return __builtin_bit_cast(unsigned, r); }
; #define WAVE_LDS_FENCE() asm volatile("s_waitcnt lgkmcnt(0)" ::: "memory")
; __device__ __forceinline__ float bf_at(const u32x4& lo, const u32x4& hi, int r) { const unsigned w = (r < 8 ? lo : hi)[(r & 7) >> 1]; return (r & 1) ? bf_hi(w) : bf_lo(w); }
; __device__ __forceinline__ void s5_out_phase(LAS unsigned char* lds, const bf16_t* UZ, const unsigned char* ws, const float* dskip, bf16_t* YG) {
;     ...
;         for (int mm = 0; mm < 4; ++mm) {
;             const int mf = mm, mb = 3 - mm;
; #pragma unroll
;             for (int nt = 0; nt < 8; ++nt) {
;                 const f32x4 z = {0.f, 0.f, 0.f, 0.f};
;                 const f32x4 cf = __builtin_amdgcn_mfma_f32_16x16x16bf16_1k(Uf[mf], Bf[0][nt], z, 0, 0, 0);
;                 const f32x4 cb = __builtin_amdgcn_mfma_f32_16x16x16bf16_1k(Uf[mb], Bf[1][nt], z, 0, 0, 0);
;                 u32x2 wf, wb; wf.x = pk2(cf[0], cf[1]); wf.y = pk2(cf[2], cf[3]); wb.x = pk2(cb[0], cb[1]); wb.y = pk2(cb[2], cb[3]);
;                 *(LAS u32x2*)(wl + nt * 640 + wofs) = wf;
;                 *(LAS u32x2*)(wl + BUT_BYTES + nt * 640 + wofs) = wb;
;             }
;             WAVE_LDS_FENCE();
;             const LAS unsigned char* rp = wl + lane * 80;
;             const u32x4 fre0 = *(const LAS u32x4*)(rp), fre1 = *(const LAS u32x4*)(rp + 16), fim0 = *(const LAS u32x4*)(rp + 32), fim1 = *(const LAS u32x4*)(rp + 48);
;             const u32x4 bre0 = *(const LAS u32x4*)(rp + BUT_BYTES), bre1 = *(const LAS u32x4*)(rp + BUT_BYTES + 16), bim0 = *(const LAS u32x4*)(rp + BUT_BYTES + 32), bim1 = *(const LAS u32x4*)(rp + BUT_BYTES + 48);
;             LAS unsigned char* xf = wl + 2 * BUT_BYTES; LAS unsigned char* xbk = xf + XB_BYTES;
; #pragma unroll
;             for (int rr = 0; rr < 16; ++rr) {
;                 const int r = rr, rb = 15 - rr;
;                 { const f32x2 bb = {bf_at(fre0, fre1, r), bf_at(fim0, fim1, r)};
;                   const f32x2 n2 = cmac((f32x2){xfr, xfi}, (f32x2){ap[0].x, ap[0].x}, (f32x2){-ap[0].y, ap[0].y}, bb); xfr = n2.x; xfi = n2.y;
.LBB0_755:
	v_mov_b32_e32 v114, v44
	v_mov_b32_e32 v119, v45
	v_mov_b32_e32 v121, v46
	v_mov_b32_e32 v127, v47
	v_mfma_f32_4x4x4_16b_bf16 v[188:191], v[172:173], v[60:61], 0 cbsz:4 abid:0
	v_mfma_f32_4x4x4_16b_bf16 v[194:197], v[172:173], v[68:69], 0 cbsz:4 abid:0
	v_mfma_f32_4x4x4_16b_bf16 v[198:201], v[172:173], v[60:61], 0 cbsz:4 abid:1
	v_mfma_f32_4x4x4_16b_bf16 v[202:205], v[172:173], v[68:69], 0 cbsz:4 abid:1
	v_mfma_f32_4x4x4_16b_bf16 v[206:209], v[172:173], v[60:61], 0 cbsz:4 abid:2
	v_mfma_f32_4x4x4_16b_bf16 v[210:213], v[172:173], v[68:69], 0 cbsz:4 abid:2
	v_mfma_f32_4x4x4_16b_bf16 v[214:217], v[172:173], v[60:61], 0 cbsz:4 abid:3
	v_mfma_f32_4x4x4_16b_bf16 v[218:221], v[172:173], v[68:69], 0 cbsz:4 abid:3
	v_mfma_f32_4x4x4_16b_bf16 v[222:225], v[116:117], v[76:77], 0 cbsz:4 abid:0
	v_mfma_f32_4x4x4_16b_bf16 v[226:229], v[116:117], v[84:85], 0 cbsz:4 abid:0
	v_mfma_f32_4x4x4_16b_bf16 v[230:233], v[116:117], v[76:77], 0 cbsz:4 abid:1
	v_mfma_f32_4x4x4_16b_bf16 v[234:237], v[116:117], v[84:85], 0 cbsz:4 abid:1
	v_mfma_f32_4x4x4_16b_bf16 v[238:241], v[116:117], v[76:77], 0 cbsz:4 abid:2
	v_mfma_f32_4x4x4_16b_bf16 v[242:245], v[116:117], v[84:85], 0 cbsz:4 abid:2
	v_mfma_f32_4x4x4_16b_bf16 v[246:249], v[116:117], v[76:77], 0 cbsz:4 abid:3
	v_mfma_f32_4x4x4_16b_bf16 v[250:253], v[116:117], v[84:85], 0 cbsz:4 abid:3
	v_mfma_f32_4x4x4_16b_bf16 v[188:191], v[172:173], v[62:63], v[188:191] cbsz:4 abid:4
	v_mfma_f32_4x4x4_16b_bf16 v[194:197], v[172:173], v[70:71], v[194:197] cbsz:4 abid:4
	v_mfma_f32_4x4x4_16b_bf16 v[198:201], v[172:173], v[62:63], v[198:201] cbsz:4 abid:5
	v_mfma_f32_4x4x4_16b_bf16 v[202:205], v[172:173], v[70:71], v[202:205] cbsz:4 abid:5
	v_mfma_f32_4x4x4_16b_bf16 v[206:209], v[172:173], v[62:63], v[206:209] cbsz:4 abid:6
	v_mfma_f32_4x4x4_16b_bf16 v[210:213], v[172:173], v[70:71], v[210:213] cbsz:4 abid:6
	v_mfma_f32_4x4x4_16b_bf16 v[214:217], v[172:173], v[62:63], v[214:217] cbsz:4 abid:7
	v_mfma_f32_4x4x4_16b_bf16 v[218:221], v[172:173], v[70:71], v[218:221] cbsz:4 abid:7
	v_mfma_f32_4x4x4_16b_bf16 v[222:225], v[116:117], v[78:79], v[222:225] cbsz:4 abid:4
	v_mfma_f32_4x4x4_16b_bf16 v[226:229], v[116:117], v[86:87], v[226:229] cbsz:4 abid:4
	v_mfma_f32_4x4x4_16b_bf16 v[230:233], v[116:117], v[78:79], v[230:233] cbsz:4 abid:5
	v_mfma_f32_4x4x4_16b_bf16 v[234:237], v[116:117], v[86:87], v[234:237] cbsz:4 abid:5
	v_mfma_f32_4x4x4_16b_bf16 v[238:241], v[116:117], v[78:79], v[238:241] cbsz:4 abid:6
	v_mfma_f32_4x4x4_16b_bf16 v[242:245], v[116:117], v[86:87], v[242:245] cbsz:4 abid:6
	v_mfma_f32_4x4x4_16b_bf16 v[246:249], v[116:117], v[78:79], v[246:249] cbsz:4 abid:7
	v_mfma_f32_4x4x4_16b_bf16 v[250:253], v[116:117], v[86:87], v[250:253] cbsz:4 abid:7
	v_mfma_f32_4x4x4_16b_bf16 v[188:191], v[172:173], v[64:65], v[188:191] cbsz:4 abid:8
	v_mfma_f32_4x4x4_16b_bf16 v[194:197], v[172:173], v[72:73], v[194:197] cbsz:4 abid:8
	v_mfma_f32_4x4x4_16b_bf16 v[198:201], v[172:173], v[64:65], v[198:201] cbsz:4 abid:9
	v_mfma_f32_4x4x4_16b_bf16 v[202:205], v[172:173], v[72:73], v[202:205] cbsz:4 abid:9
	v_mfma_f32_4x4x4_16b_bf16 v[206:209], v[172:173], v[64:65], v[206:209] cbsz:4 abid:10
	v_mfma_f32_4x4x4_16b_bf16 v[210:213], v[172:173], v[72:73], v[210:213] cbsz:4 abid:10
	v_mfma_f32_4x4x4_16b_bf16 v[214:217], v[172:173], v[64:65], v[214:217] cbsz:4 abid:11
	v_mfma_f32_4x4x4_16b_bf16 v[218:221], v[172:173], v[72:73], v[218:221] cbsz:4 abid:11
	v_mfma_f32_4x4x4_16b_bf16 v[222:225], v[116:117], v[80:81], v[222:225] cbsz:4 abid:8
	v_mfma_f32_4x4x4_16b_bf16 v[226:229], v[116:117], v[88:89], v[226:229] cbsz:4 abid:8
	v_mfma_f32_4x4x4_16b_bf16 v[230:233], v[116:117], v[80:81], v[230:233] cbsz:4 abid:9
	v_mfma_f32_4x4x4_16b_bf16 v[234:237], v[116:117], v[88:89], v[234:237] cbsz:4 abid:9
	v_mfma_f32_4x4x4_16b_bf16 v[238:241], v[116:117], v[80:81], v[238:241] cbsz:4 abid:10
	v_mfma_f32_4x4x4_16b_bf16 v[242:245], v[116:117], v[88:89], v[242:245] cbsz:4 abid:10
	v_mfma_f32_4x4x4_16b_bf16 v[246:249], v[116:117], v[80:81], v[246:249] cbsz:4 abid:11
	v_mfma_f32_4x4x4_16b_bf16 v[250:253], v[116:117], v[88:89], v[250:253] cbsz:4 abid:11
	v_mfma_f32_4x4x4_16b_bf16 v[188:191], v[172:173], v[66:67], v[188:191] cbsz:4 abid:12
	v_mfma_f32_4x4x4_16b_bf16 v[194:197], v[172:173], v[74:75], v[194:197] cbsz:4 abid:12
	v_mfma_f32_4x4x4_16b_bf16 v[198:201], v[172:173], v[66:67], v[198:201] cbsz:4 abid:13
	v_mfma_f32_4x4x4_16b_bf16 v[202:205], v[172:173], v[74:75], v[202:205] cbsz:4 abid:13
	v_mfma_f32_4x4x4_16b_bf16 v[206:209], v[172:173], v[66:67], v[206:209] cbsz:4 abid:14
	v_mfma_f32_4x4x4_16b_bf16 v[210:213], v[172:173], v[74:75], v[210:213] cbsz:4 abid:14
	v_mfma_f32_4x4x4_16b_bf16 v[214:217], v[172:173], v[66:67], v[214:217] cbsz:4 abid:15
	v_mfma_f32_4x4x4_16b_bf16 v[218:221], v[172:173], v[74:75], v[218:221] cbsz:4 abid:15
	v_mfma_f32_4x4x4_16b_bf16 v[222:225], v[116:117], v[82:83], v[222:225] cbsz:4 abid:12
	v_mfma_f32_4x4x4_16b_bf16 v[226:229], v[116:117], v[90:91], v[226:229] cbsz:4 abid:12
	v_mfma_f32_4x4x4_16b_bf16 v[230:233], v[116:117], v[82:83], v[230:233] cbsz:4 abid:13
	v_mfma_f32_4x4x4_16b_bf16 v[234:237], v[116:117], v[90:91], v[234:237] cbsz:4 abid:13
	v_mfma_f32_4x4x4_16b_bf16 v[238:241], v[116:117], v[82:83], v[238:241] cbsz:4 abid:14
	v_mfma_f32_4x4x4_16b_bf16 v[242:245], v[116:117], v[90:91], v[242:245] cbsz:4 abid:14
	v_mfma_f32_4x4x4_16b_bf16 v[246:249], v[116:117], v[82:83], v[246:249] cbsz:4 abid:15
	v_mfma_f32_4x4x4_16b_bf16 v[250:253], v[116:117], v[90:91], v[250:253] cbsz:4 abid:15
	v_fma_f32 v188, v150, v114, v188
	v_fma_f32 v194, v150, v119, v194
	v_fma_f32 v188, v16, v119, v188
	v_fma_f32 v194, v17, v114, v194
; #define LAS __attribute__((address_space(3)))
; __device__ __forceinline__ unsigned pk2(float lo, float hi) { f32x2 v = {lo, hi}; nbf2 r = __builtin_convertvector(v, nbf2); return __builtin_bit_cast(unsigned, r); }
; #define WAVE_LDS_FENCE() asm volatile("s_waitcnt lgkmcnt(0)" ::: "memory")
; __device__ __forceinline__ float bf_at(const u32x4& lo, const u32x4& hi, int r) { const unsigned w = (r < 8 ? lo : hi)[(r & 7) >> 1]; return (r & 1) ? bf_hi(w) : bf_lo(w); }
; __device__ __forceinline__ void s5_out_phase(LAS unsigned char* lds, const bf16_t* UZ, const unsigned char* ws, const float* dskip, bf16_t* YG) {
;     ...
; #pragma unroll
;             for (int rr = 0; rr < 16; ++rr) {
;                 const int r = rr, rb = 15 - rr;
;                 { const f32x2 bb = {bf_at(fre0, fre1, r), bf_at(fim0, fim1, r)};
;                   const f32x2 n2 = cmac((f32x2){xfr, xfi}, (f32x2){ap[0].x, ap[0].x}, (f32x2){-ap[0].y, ap[0].y}, bb); xfr = n2.x; xfi = n2.y;
;                   *(LAS unsigned*)(xf + r * XB_PITCH + lane * 4) = pk2(n2.x, n2.y); }
;                 { const f32x2 bb = {bf_at(bre0, bre1, rb), bf_at(bim0, bim1, rb)};
;                   const f32x2 n2 = cmac((f32x2){xbr, xbi}, (f32x2){ap[1].x, ap[1].x}, (f32x2){-ap[1].y, ap[1].y}, bb); xbr = n2.x; xbi = n2.y;
;                   *(LAS unsigned*)(xbk + rb * XB_PITCH + lane * 4) = pk2(n2.x, n2.y); }
;             }
;             WAVE_LDS_FENCE();
; #pragma unroll
;             for (int ks = 0; ks < 4; ++ks) {
;                 const bf16x8 Xf = *(const LAS bf16x8*)(xf + fr * XB_PITCH + (8 * fq + 32 * ks) * 2);
;                 const bf16x8 Xb = *(const LAS bf16x8*)(xbk + fr * XB_PITCH + (8 * fq + 32 * ks) * 2);
	v_fma_f32 v249, v152, v121, v249
	v_fma_f32 v253, v152, v127, v253
	v_fma_f32 v249, v36, v127, v249
	v_fma_f32 v253, v37, v121, v253
	v_cvt_pk_bf16_f32 v128, v188, v194
	v_cvt_pk_bf16_f32 v136, v249, v253
	v_add_u32_e32 v193, 0x2800, v103
	v_add_u32_e32 v254, 0x45c0, v103
	v_fma_f32 v189, v150, v188, v189
	v_fma_f32 v195, v150, v194, v195
	v_fma_f32 v189, v16, v194, v189
	v_fma_f32 v195, v17, v188, v195
	v_fma_f32 v248, v152, v249, v248
	v_fma_f32 v252, v152, v253, v252
	v_fma_f32 v248, v36, v253, v248
	v_fma_f32 v252, v37, v249, v252
	v_cvt_pk_bf16_f32 v131, v189, v195
	v_cvt_pk_bf16_f32 v139, v248, v252
	ds_write2_b32 v193, v128, v131 offset0:0 offset1:68
	ds_write2_b32 v254, v139, v136 offset0:136 offset1:204
	v_fma_f32 v190, v150, v189, v190
	v_fma_f32 v196, v150, v195, v196
	v_fma_f32 v190, v16, v195, v190
	v_fma_f32 v196, v17, v189, v196
	v_fma_f32 v247, v152, v248, v247
	v_fma_f32 v251, v152, v252, v251
	v_fma_f32 v247, v36, v252, v247
	v_fma_f32 v251, v37, v248, v251
	v_cvt_pk_bf16_f32 v132, v190, v196
	v_cvt_pk_bf16_f32 v143, v247, v251
	v_fma_f32 v191, v150, v190, v191
	v_fma_f32 v197, v150, v196, v197
	v_fma_f32 v191, v16, v196, v191
	v_fma_f32 v197, v17, v190, v197
	v_fma_f32 v246, v152, v247, v246
	v_fma_f32 v250, v152, v251, v250
	v_fma_f32 v246, v36, v251, v246
	v_fma_f32 v250, v37, v247, v250
	v_cvt_pk_bf16_f32 v135, v191, v197
	v_cvt_pk_bf16_f32 v187, v246, v250
	ds_write2_b32 v193, v132, v135 offset0:136 offset1:204
	ds_write2_b32 v254, v187, v143 offset0:0 offset1:68
	v_fma_f32 v198, v150, v191, v198
	v_fma_f32 v202, v150, v197, v202
	v_fma_f32 v198, v16, v197, v198
	v_fma_f32 v202, v17, v191, v202
	v_fma_f32 v241, v152, v246, v241
	v_fma_f32 v245, v152, v250, v245
	v_fma_f32 v241, v36, v250, v241
	v_fma_f32 v245, v37, v246, v245
	v_cvt_pk_bf16_f32 v128, v198, v202
	v_cvt_pk_bf16_f32 v136, v241, v245
	v_add_u32_e32 v193, 0x2c40, v103
	v_add_u32_e32 v254, 0x4180, v103
	v_fma_f32 v199, v150, v198, v199
	v_fma_f32 v203, v150, v202, v203
	v_fma_f32 v199, v16, v202, v199
	v_fma_f32 v203, v17, v198, v203
	v_fma_f32 v240, v152, v241, v240
	v_fma_f32 v244, v152, v245, v244
	v_fma_f32 v240, v36, v245, v240
	v_fma_f32 v244, v37, v241, v244
	v_cvt_pk_bf16_f32 v131, v199, v203
	v_cvt_pk_bf16_f32 v139, v240, v244
	ds_write2_b32 v193, v128, v131 offset0:0 offset1:68
	ds_write2_b32 v254, v139, v136 offset0:136 offset1:204
	v_fma_f32 v200, v150, v199, v200
	v_fma_f32 v204, v150, v203, v204
	v_fma_f32 v200, v16, v203, v200
	v_fma_f32 v204, v17, v199, v204
	v_fma_f32 v239, v152, v240, v239
	v_fma_f32 v243, v152, v244, v243
	v_fma_f32 v239, v36, v244, v239
	v_fma_f32 v243, v37, v240, v243
	v_cvt_pk_bf16_f32 v132, v200, v204
	v_cvt_pk_bf16_f32 v143, v239, v243
	v_fma_f32 v201, v150, v200, v201
	v_fma_f32 v205, v150, v204, v205
	v_fma_f32 v201, v16, v204, v201
	v_fma_f32 v205, v17, v200, v205
	v_fma_f32 v238, v152, v239, v238
	v_fma_f32 v242, v152, v243, v242
	v_fma_f32 v238, v36, v243, v238
	v_fma_f32 v242, v37, v239, v242
	v_cvt_pk_bf16_f32 v135, v201, v205
	v_cvt_pk_bf16_f32 v187, v238, v242
	ds_write2_b32 v193, v132, v135 offset0:136 offset1:204
	ds_write2_b32 v254, v187, v143 offset0:0 offset1:68
	v_fma_f32 v206, v150, v201, v206
	v_fma_f32 v210, v150, v205, v210
	v_fma_f32 v206, v16, v205, v206
	v_fma_f32 v210, v17, v201, v210
	v_fma_f32 v233, v152, v238, v233
	v_fma_f32 v237, v152, v242, v237
	v_fma_f32 v233, v36, v242, v233
	v_fma_f32 v237, v37, v238, v237
	v_cvt_pk_bf16_f32 v128, v206, v210
	v_cvt_pk_bf16_f32 v136, v233, v237
	v_add_u32_e32 v193, 0x3080, v103
	v_add_u32_e32 v254, 0x3d40, v103
	v_fma_f32 v207, v150, v206, v207
	v_fma_f32 v211, v150, v210, v211
	v_fma_f32 v207, v16, v210, v207
	v_fma_f32 v211, v17, v206, v211
	v_fma_f32 v232, v152, v233, v232
	v_fma_f32 v236, v152, v237, v236
	v_fma_f32 v232, v36, v237, v232
	v_fma_f32 v236, v37, v233, v236
	v_cvt_pk_bf16_f32 v131, v207, v211
	v_cvt_pk_bf16_f32 v139, v232, v236
	ds_write2_b32 v193, v128, v131 offset0:0 offset1:68
	ds_write2_b32 v254, v139, v136 offset0:136 offset1:204
	v_fma_f32 v208, v150, v207, v208
	v_fma_f32 v212, v150, v211, v212
	v_fma_f32 v208, v16, v211, v208
	v_fma_f32 v212, v17, v207, v212
	v_fma_f32 v231, v152, v232, v231
	v_fma_f32 v235, v152, v236, v235
	v_fma_f32 v231, v36, v236, v231
	v_fma_f32 v235, v37, v232, v235
	v_cvt_pk_bf16_f32 v132, v208, v212
	v_cvt_pk_bf16_f32 v143, v231, v235
	v_fma_f32 v209, v150, v208, v209
	v_fma_f32 v213, v150, v212, v213
	v_fma_f32 v209, v16, v212, v209
	v_fma_f32 v213, v17, v208, v213
	v_fma_f32 v230, v152, v231, v230
	v_fma_f32 v234, v152, v235, v234
	v_fma_f32 v230, v36, v235, v230
	v_fma_f32 v234, v37, v231, v234
	v_cvt_pk_bf16_f32 v135, v209, v213
	v_cvt_pk_bf16_f32 v187, v230, v234
	ds_write2_b32 v193, v132, v135 offset0:136 offset1:204
	ds_write2_b32 v254, v187, v143 offset0:0 offset1:68
	v_fma_f32 v214, v150, v209, v214
	v_fma_f32 v218, v150, v213, v218
	v_fma_f32 v214, v16, v213, v214
	v_fma_f32 v218, v17, v209, v218
	v_fma_f32 v225, v152, v230, v225
	v_fma_f32 v229, v152, v234, v229
	v_fma_f32 v225, v36, v234, v225
	v_fma_f32 v229, v37, v230, v229
	v_cvt_pk_bf16_f32 v128, v214, v218
	v_cvt_pk_bf16_f32 v136, v225, v229
	v_add_u32_e32 v193, 0x34c0, v103
	v_add_u32_e32 v254, 0x3900, v103
	v_fma_f32 v215, v150, v214, v215
	v_fma_f32 v219, v150, v218, v219
	v_fma_f32 v215, v16, v218, v215
	v_fma_f32 v219, v17, v214, v219
	v_fma_f32 v224, v152, v225, v224
	v_fma_f32 v228, v152, v229, v228
	v_fma_f32 v224, v36, v229, v224
	v_fma_f32 v228, v37, v225, v228
	v_cvt_pk_bf16_f32 v131, v215, v219
	v_cvt_pk_bf16_f32 v139, v224, v228
	ds_write2_b32 v193, v128, v131 offset0:0 offset1:68
	ds_write2_b32 v254, v139, v136 offset0:136 offset1:204
	v_fma_f32 v216, v150, v215, v216
	v_fma_f32 v220, v150, v219, v220
	v_fma_f32 v216, v16, v219, v216
	v_fma_f32 v220, v17, v215, v220
	v_fma_f32 v223, v152, v224, v223
	v_fma_f32 v227, v152, v228, v227
	v_fma_f32 v223, v36, v228, v223
	v_fma_f32 v227, v37, v224, v227
	v_cvt_pk_bf16_f32 v132, v216, v220
	v_cvt_pk_bf16_f32 v143, v223, v227
	v_fma_f32 v217, v150, v216, v217
	v_fma_f32 v221, v150, v220, v221
	v_fma_f32 v217, v16, v220, v217
	v_fma_f32 v221, v17, v216, v221
	v_fma_f32 v222, v152, v223, v222
	v_fma_f32 v226, v152, v227, v226
	v_fma_f32 v222, v36, v227, v222
	v_fma_f32 v226, v37, v223, v226
	v_cvt_pk_bf16_f32 v135, v217, v221
	v_cvt_pk_bf16_f32 v187, v222, v226
	ds_write2_b32 v193, v132, v135 offset0:136 offset1:204
	ds_write2_b32 v254, v187, v143 offset0:0 offset1:68
	v_mov_b32_e32 v114, v217
	v_mov_b32_e32 v119, v221
	v_mov_b32_e32 v121, v222
	v_mov_b32_e32 v127, v226
	ds_read_b128 v[188:191], v110 offset:10240
	ds_read_b128 v[194:197], v110 offset:10304
	ds_read_b128 v[198:201], v110 offset:10368
	ds_read_b128 v[202:205], v110 offset:10432
	ds_read_b128 v[206:209], v110 offset:14592
	ds_read_b128 v[210:213], v110 offset:14656
	ds_read_b128 v[214:217], v110 offset:14720
	ds_read_b128 v[218:221], v110 offset:14784
	s_waitcnt lgkmcnt(7)
; #define LAS __attribute__((address_space(3)))
; __device__ __forceinline__ unsigned pk2(float lo, float hi) { f32x2 v = {lo, hi}; nbf2 r = __builtin_convertvector(v, nbf2); return __builtin_bit_cast(unsigned, r); }
; __device__ __forceinline__ void s5_out_phase(LAS unsigned char* lds, const bf16_t* UZ, const unsigned char* ws, const float* dskip, bf16_t* YG) {
;     ...
; #pragma unroll
;             for (int nt = 0; nt < 8; ++nt) {
;                 const f32x4 z = {0.f, 0.f, 0.f, 0.f};
;                 const f32x4 cf = __builtin_amdgcn_mfma_f32_16x16x16bf16_1k(Uf[mf], Bf[0][nt], z, 0, 0, 0);
;                 const f32x4 cb = __builtin_amdgcn_mfma_f32_16x16x16bf16_1k(Uf[mb], Bf[1][nt], z, 0, 0, 0);
;                 u32x2 wf, wb; wf.x = pk2(cf[0], cf[1]); wf.y = pk2(cf[2], cf[3]); wb.x = pk2(cb[0], cb[1]); wb.y = pk2(cb[2], cb[3]);
;                 *(LAS u32x2*)(wl + nt * 640 + wofs) = wf;
;                 *(LAS u32x2*)(wl + BUT_BYTES + nt * 640 + wofs) = wb;
;             }
;     ...
; #pragma unroll
;             for (int ks = 0; ks < 4; ++ks) {
;                 const bf16x8 Xf = *(const LAS bf16x8*)(xf + fr * XB_PITCH + (8 * fq + 32 * ks) * 2);
;                 const bf16x8 Xb = *(const LAS bf16x8*)(xbk + fr * XB_PITCH + (8 * fq + 32 * ks) * 2);
;                 accY[mf] = __builtin_amdgcn_mfma_f32_16x16x32_bf16(Cf[0][ks], Xf, accY[mf], 0, 0, 0);
;                 accY[mb] = __builtin_amdgcn_mfma_f32_16x16x32_bf16(Cf[1][ks], Xb, accY[mb], 0, 0, 0);
;             }
	v_mfma_f32_16x16x32_bf16 v[48:51], v[0:3], v[188:191], 0
	s_waitcnt lgkmcnt(3)
	v_mfma_f32_16x16x32_bf16 v[44:47], v[20:23], v[206:209], 0
	v_mfma_f32_16x16x32_bf16 v[48:51], v[4:7], v[194:197], v[48:51]
	s_waitcnt lgkmcnt(2)
	v_mfma_f32_16x16x32_bf16 v[44:47], v[24:27], v[210:213], v[44:47]
	v_mfma_f32_16x16x32_bf16 v[48:51], v[8:11], v[198:201], v[48:51]
	s_waitcnt lgkmcnt(1)
	v_mfma_f32_16x16x32_bf16 v[44:47], v[28:31], v[214:217], v[44:47]
	v_mfma_f32_16x16x32_bf16 v[48:51], v[12:15], v[202:205], v[48:51]
	s_waitcnt lgkmcnt(0)
	v_mfma_f32_16x16x32_bf16 v[44:47], v[32:35], v[218:221], v[44:47]
	v_mfma_f32_4x4x4_16b_bf16 v[188:191], v[170:171], v[60:61], 0 cbsz:4 abid:0
	v_mfma_f32_4x4x4_16b_bf16 v[194:197], v[170:171], v[68:69], 0 cbsz:4 abid:0
	v_mfma_f32_4x4x4_16b_bf16 v[198:201], v[170:171], v[60:61], 0 cbsz:4 abid:1
	v_mfma_f32_4x4x4_16b_bf16 v[202:205], v[170:171], v[68:69], 0 cbsz:4 abid:1
	v_mfma_f32_4x4x4_16b_bf16 v[206:209], v[170:171], v[60:61], 0 cbsz:4 abid:2
	v_mfma_f32_4x4x4_16b_bf16 v[210:213], v[170:171], v[68:69], 0 cbsz:4 abid:2
	v_mfma_f32_4x4x4_16b_bf16 v[214:217], v[170:171], v[60:61], 0 cbsz:4 abid:3
	v_mfma_f32_4x4x4_16b_bf16 v[218:221], v[170:171], v[68:69], 0 cbsz:4 abid:3
	v_mfma_f32_4x4x4_16b_bf16 v[222:225], v[168:169], v[76:77], 0 cbsz:4 abid:0
	v_mfma_f32_4x4x4_16b_bf16 v[226:229], v[168:169], v[84:85], 0 cbsz:4 abid:0
	v_mfma_f32_4x4x4_16b_bf16 v[230:233], v[168:169], v[76:77], 0 cbsz:4 abid:1
	v_mfma_f32_4x4x4_16b_bf16 v[234:237], v[168:169], v[84:85], 0 cbsz:4 abid:1
	v_mfma_f32_4x4x4_16b_bf16 v[238:241], v[168:169], v[76:77], 0 cbsz:4 abid:2
	v_mfma_f32_4x4x4_16b_bf16 v[242:245], v[168:169], v[84:85], 0 cbsz:4 abid:2
	v_mfma_f32_4x4x4_16b_bf16 v[246:249], v[168:169], v[76:77], 0 cbsz:4 abid:3
	v_mfma_f32_4x4x4_16b_bf16 v[250:253], v[168:169], v[84:85], 0 cbsz:4 abid:3
	v_mfma_f32_4x4x4_16b_bf16 v[188:191], v[170:171], v[62:63], v[188:191] cbsz:4 abid:4
	v_mfma_f32_4x4x4_16b_bf16 v[194:197], v[170:171], v[70:71], v[194:197] cbsz:4 abid:4
	v_mfma_f32_4x4x4_16b_bf16 v[198:201], v[170:171], v[62:63], v[198:201] cbsz:4 abid:5
	v_mfma_f32_4x4x4_16b_bf16 v[202:205], v[170:171], v[70:71], v[202:205] cbsz:4 abid:5
	v_mfma_f32_4x4x4_16b_bf16 v[206:209], v[170:171], v[62:63], v[206:209] cbsz:4 abid:6
	v_mfma_f32_4x4x4_16b_bf16 v[210:213], v[170:171], v[70:71], v[210:213] cbsz:4 abid:6
	v_mfma_f32_4x4x4_16b_bf16 v[214:217], v[170:171], v[62:63], v[214:217] cbsz:4 abid:7
	v_mfma_f32_4x4x4_16b_bf16 v[218:221], v[170:171], v[70:71], v[218:221] cbsz:4 abid:7
	v_mfma_f32_4x4x4_16b_bf16 v[222:225], v[168:169], v[78:79], v[222:225] cbsz:4 abid:4
	v_mfma_f32_4x4x4_16b_bf16 v[226:229], v[168:169], v[86:87], v[226:229] cbsz:4 abid:4
	v_mfma_f32_4x4x4_16b_bf16 v[230:233], v[168:169], v[78:79], v[230:233] cbsz:4 abid:5
	v_mfma_f32_4x4x4_16b_bf16 v[234:237], v[168:169], v[86:87], v[234:237] cbsz:4 abid:5
	v_mfma_f32_4x4x4_16b_bf16 v[238:241], v[168:169], v[78:79], v[238:241] cbsz:4 abid:6
	v_mfma_f32_4x4x4_16b_bf16 v[242:245], v[168:169], v[86:87], v[242:245] cbsz:4 abid:6
	v_mfma_f32_4x4x4_16b_bf16 v[246:249], v[168:169], v[78:79], v[246:249] cbsz:4 abid:7
	v_mfma_f32_4x4x4_16b_bf16 v[250:253], v[168:169], v[86:87], v[250:253] cbsz:4 abid:7
	v_mfma_f32_4x4x4_16b_bf16 v[188:191], v[170:171], v[64:65], v[188:191] cbsz:4 abid:8
	v_mfma_f32_4x4x4_16b_bf16 v[194:197], v[170:171], v[72:73], v[194:197] cbsz:4 abid:8
	v_mfma_f32_4x4x4_16b_bf16 v[198:201], v[170:171], v[64:65], v[198:201] cbsz:4 abid:9
	v_mfma_f32_4x4x4_16b_bf16 v[202:205], v[170:171], v[72:73], v[202:205] cbsz:4 abid:9
	v_mfma_f32_4x4x4_16b_bf16 v[206:209], v[170:171], v[64:65], v[206:209] cbsz:4 abid:10
	v_mfma_f32_4x4x4_16b_bf16 v[210:213], v[170:171], v[72:73], v[210:213] cbsz:4 abid:10
	v_mfma_f32_4x4x4_16b_bf16 v[214:217], v[170:171], v[64:65], v[214:217] cbsz:4 abid:11
	v_mfma_f32_4x4x4_16b_bf16 v[218:221], v[170:171], v[72:73], v[218:221] cbsz:4 abid:11
	v_mfma_f32_4x4x4_16b_bf16 v[222:225], v[168:169], v[80:81], v[222:225] cbsz:4 abid:8
	v_mfma_f32_4x4x4_16b_bf16 v[226:229], v[168:169], v[88:89], v[226:229] cbsz:4 abid:8
	v_mfma_f32_4x4x4_16b_bf16 v[230:233], v[168:169], v[80:81], v[230:233] cbsz:4 abid:9
	v_mfma_f32_4x4x4_16b_bf16 v[234:237], v[168:169], v[88:89], v[234:237] cbsz:4 abid:9
	v_mfma_f32_4x4x4_16b_bf16 v[238:241], v[168:169], v[80:81], v[238:241] cbsz:4 abid:10
	v_mfma_f32_4x4x4_16b_bf16 v[242:245], v[168:169], v[88:89], v[242:245] cbsz:4 abid:10
	v_mfma_f32_4x4x4_16b_bf16 v[246:249], v[168:169], v[80:81], v[246:249] cbsz:4 abid:11
	v_mfma_f32_4x4x4_16b_bf16 v[250:253], v[168:169], v[88:89], v[250:253] cbsz:4 abid:11
	v_mfma_f32_4x4x4_16b_bf16 v[188:191], v[170:171], v[66:67], v[188:191] cbsz:4 abid:12
	v_mfma_f32_4x4x4_16b_bf16 v[194:197], v[170:171], v[74:75], v[194:197] cbsz:4 abid:12
	v_mfma_f32_4x4x4_16b_bf16 v[198:201], v[170:171], v[66:67], v[198:201] cbsz:4 abid:13
	v_mfma_f32_4x4x4_16b_bf16 v[202:205], v[170:171], v[74:75], v[202:205] cbsz:4 abid:13
	v_mfma_f32_4x4x4_16b_bf16 v[206:209], v[170:171], v[66:67], v[206:209] cbsz:4 abid:14
	v_mfma_f32_4x4x4_16b_bf16 v[210:213], v[170:171], v[74:75], v[210:213] cbsz:4 abid:14
	v_mfma_f32_4x4x4_16b_bf16 v[214:217], v[170:171], v[66:67], v[214:217] cbsz:4 abid:15
	v_mfma_f32_4x4x4_16b_bf16 v[218:221], v[170:171], v[74:75], v[218:221] cbsz:4 abid:15
	v_mfma_f32_4x4x4_16b_bf16 v[222:225], v[168:169], v[82:83], v[222:225] cbsz:4 abid:12
	v_mfma_f32_4x4x4_16b_bf16 v[226:229], v[168:169], v[90:91], v[226:229] cbsz:4 abid:12
	v_mfma_f32_4x4x4_16b_bf16 v[230:233], v[168:169], v[82:83], v[230:233] cbsz:4 abid:13
	v_mfma_f32_4x4x4_16b_bf16 v[234:237], v[168:169], v[90:91], v[234:237] cbsz:4 abid:13
; #define LAS __attribute__((address_space(3)))
; __device__ __forceinline__ unsigned pk2(float lo, float hi) { f32x2 v = {lo, hi}; nbf2 r = __builtin_convertvector(v, nbf2); return __builtin_bit_cast(unsigned, r); }
; __device__ __forceinline__ void s5_out_phase(LAS unsigned char* lds, const bf16_t* UZ, const unsigned char* ws, const float* dskip, bf16_t* YG) {
;     ...
; #pragma unroll
;             for (int nt = 0; nt < 8; ++nt) {
;                 const f32x4 z = {0.f, 0.f, 0.f, 0.f};
;                 const f32x4 cf = __builtin_amdgcn_mfma_f32_16x16x16bf16_1k(Uf[mf], Bf[0][nt], z, 0, 0, 0);
;                 const f32x4 cb = __builtin_amdgcn_mfma_f32_16x16x16bf16_1k(Uf[mb], Bf[1][nt], z, 0, 0, 0);
;                 u32x2 wf, wb; wf.x = pk2(cf[0], cf[1]); wf.y = pk2(cf[2], cf[3]); wb.x = pk2(cb[0], cb[1]); wb.y = pk2(cb[2], cb[3]);
;                 *(LAS u32x2*)(wl + nt * 640 + wofs) = wf;
;                 *(LAS u32x2*)(wl + BUT_BYTES + nt * 640 + wofs) = wb;
;             }
;             WAVE_LDS_FENCE();
;             const LAS unsigned char* rp = wl + lane * 80;
;             const u32x4 fre0 = *(const LAS u32x4*)(rp), fre1 = *(const LAS u32x4*)(rp + 16), fim0 = *(const LAS u32x4*)(rp + 32), fim1 = *(const LAS u32x4*)(rp + 48);
;             const u32x4 bre0 = *(const LAS u32x4*)(rp + BUT_BYTES), bre1 = *(const LAS u32x4*)(rp + BUT_BYTES + 16), bim0 = *(const LAS u32x4*)(rp + BUT_BYTES + 32), bim1 = *(const LAS u32x4*)(rp + BUT_BYTES + 48);
;             LAS unsigned char* xf = wl + 2 * BUT_BYTES; LAS unsigned char* xbk = xf + XB_BYTES;
; #pragma unroll
;             for (int rr = 0; rr < 16; ++rr) {
;                 const int r = rr, rb = 15 - rr;
;                 { const f32x2 bb = {bf_at(fre0, fre1, r), bf_at(fim0, fim1, r)};
;                   const f32x2 n2 = cmac((f32x2){xfr, xfi}, (f32x2){ap[0].x, ap[0].x}, (f32x2){-ap[0].y, ap[0].y}, bb); xfr = n2.x; xfi = n2.y;
;                   *(LAS unsigned*)(xf + r * XB_PITCH + lane * 4) = pk2(n2.x, n2.y); }
;                 { const f32x2 bb = {bf_at(bre0, bre1, rb), bf_at(bim0, bim1, rb)};
;                   const f32x2 n2 = cmac((f32x2){xbr, xbi}, (f32x2){ap[1].x, ap[1].x}, (f32x2){-ap[1].y, ap[1].y}, bb); xbr = n2.x; xbi = n2.y;
;                   *(LAS unsigned*)(xbk + rb * XB_PITCH + lane * 4) = pk2(n2.x, n2.y); }
;             }
	v_mfma_f32_4x4x4_16b_bf16 v[238:241], v[168:169], v[82:83], v[238:241] cbsz:4 abid:14
	v_mfma_f32_4x4x4_16b_bf16 v[242:245], v[168:169], v[90:91], v[242:245] cbsz:4 abid:14
	v_mfma_f32_4x4x4_16b_bf16 v[246:249], v[168:169], v[82:83], v[246:249] cbsz:4 abid:15
	v_mfma_f32_4x4x4_16b_bf16 v[250:253], v[168:169], v[90:91], v[250:253] cbsz:4 abid:15
	v_fma_f32 v188, v150, v114, v188
	v_fma_f32 v194, v150, v119, v194
	v_fma_f32 v188, v16, v119, v188
	v_fma_f32 v194, v17, v114, v194
	v_fma_f32 v249, v152, v121, v249
	v_fma_f32 v253, v152, v127, v253
	v_fma_f32 v249, v36, v127, v249
	v_fma_f32 v253, v37, v121, v253
	v_cvt_pk_bf16_f32 v128, v188, v194
	v_cvt_pk_bf16_f32 v136, v249, v253
	v_add_u32_e32 v193, 0x2800, v103
	v_add_u32_e32 v254, 0x45c0, v103
	v_fma_f32 v189, v150, v188, v189
	v_fma_f32 v195, v150, v194, v195
	v_fma_f32 v189, v16, v194, v189
	v_fma_f32 v195, v17, v188, v195
	v_fma_f32 v248, v152, v249, v248
	v_fma_f32 v252, v152, v253, v252
	v_fma_f32 v248, v36, v253, v248
	v_fma_f32 v252, v37, v249, v252
	v_cvt_pk_bf16_f32 v131, v189, v195
	v_cvt_pk_bf16_f32 v139, v248, v252
	ds_write2_b32 v193, v128, v131 offset0:0 offset1:68
	ds_write2_b32 v254, v139, v136 offset0:136 offset1:204
	v_fma_f32 v190, v150, v189, v190
	v_fma_f32 v196, v150, v195, v196
	v_fma_f32 v190, v16, v195, v190
	v_fma_f32 v196, v17, v189, v196
	v_fma_f32 v247, v152, v248, v247
	v_fma_f32 v251, v152, v252, v251
	v_fma_f32 v247, v36, v252, v247
	v_fma_f32 v251, v37, v248, v251
	v_cvt_pk_bf16_f32 v132, v190, v196
	v_cvt_pk_bf16_f32 v143, v247, v251
	v_fma_f32 v191, v150, v190, v191
	v_fma_f32 v197, v150, v196, v197
	v_fma_f32 v191, v16, v196, v191
	v_fma_f32 v197, v17, v190, v197
	v_fma_f32 v246, v152, v247, v246
	v_fma_f32 v250, v152, v251, v250
	v_fma_f32 v246, v36, v251, v246
	v_fma_f32 v250, v37, v247, v250
	v_cvt_pk_bf16_f32 v135, v191, v197
	v_cvt_pk_bf16_f32 v187, v246, v250
	ds_write2_b32 v193, v132, v135 offset0:136 offset1:204
	ds_write2_b32 v254, v187, v143 offset0:0 offset1:68
	v_fma_f32 v198, v150, v191, v198
	v_fma_f32 v202, v150, v197, v202
	v_fma_f32 v198, v16, v197, v198
	v_fma_f32 v202, v17, v191, v202
	v_fma_f32 v241, v152, v246, v241
	v_fma_f32 v245, v152, v250, v245
	v_fma_f32 v241, v36, v250, v241
	v_fma_f32 v245, v37, v246, v245
	v_cvt_pk_bf16_f32 v128, v198, v202
	v_cvt_pk_bf16_f32 v136, v241, v245
	v_add_u32_e32 v193, 0x2c40, v103
	v_add_u32_e32 v254, 0x4180, v103
	v_fma_f32 v199, v150, v198, v199
	v_fma_f32 v203, v150, v202, v203
	v_fma_f32 v199, v16, v202, v199
	v_fma_f32 v203, v17, v198, v203
	v_fma_f32 v240, v152, v241, v240
	v_fma_f32 v244, v152, v245, v244
	v_fma_f32 v240, v36, v245, v240
	v_fma_f32 v244, v37, v241, v244
	v_cvt_pk_bf16_f32 v131, v199, v203
	v_cvt_pk_bf16_f32 v139, v240, v244
	ds_write2_b32 v193, v128, v131 offset0:0 offset1:68
	ds_write2_b32 v254, v139, v136 offset0:136 offset1:204
	v_fma_f32 v200, v150, v199, v200
	v_fma_f32 v204, v150, v203, v204
	v_fma_f32 v200, v16, v203, v200
	v_fma_f32 v204, v17, v199, v204
	v_fma_f32 v239, v152, v240, v239
	v_fma_f32 v243, v152, v244, v243
	v_fma_f32 v239, v36, v244, v239
	v_fma_f32 v243, v37, v240, v243
	v_cvt_pk_bf16_f32 v132, v200, v204
	v_cvt_pk_bf16_f32 v143, v239, v243
	v_fma_f32 v201, v150, v200, v201
	v_fma_f32 v205, v150, v204, v205
	v_fma_f32 v201, v16, v204, v201
	v_fma_f32 v205, v17, v200, v205
	v_fma_f32 v238, v152, v239, v238
	v_fma_f32 v242, v152, v243, v242
	v_fma_f32 v238, v36, v243, v238
	v_fma_f32 v242, v37, v239, v242
	v_cvt_pk_bf16_f32 v135, v201, v205
	v_cvt_pk_bf16_f32 v187, v238, v242
	ds_write2_b32 v193, v132, v135 offset0:136 offset1:204
	ds_write2_b32 v254, v187, v143 offset0:0 offset1:68
	v_fma_f32 v206, v150, v201, v206
	v_fma_f32 v210, v150, v205, v210
	v_fma_f32 v206, v16, v205, v206
	v_fma_f32 v210, v17, v201, v210
	v_fma_f32 v233, v152, v238, v233
	v_fma_f32 v237, v152, v242, v237
	v_fma_f32 v233, v36, v242, v233
	v_fma_f32 v237, v37, v238, v237
	v_cvt_pk_bf16_f32 v128, v206, v210
	v_cvt_pk_bf16_f32 v136, v233, v237
	v_add_u32_e32 v193, 0x3080, v103
	v_add_u32_e32 v254, 0x3d40, v103
	v_fma_f32 v207, v150, v206, v207
	v_fma_f32 v211, v150, v210, v211
	v_fma_f32 v207, v16, v210, v207
	v_fma_f32 v211, v17, v206, v211
	v_fma_f32 v232, v152, v233, v232
	v_fma_f32 v236, v152, v237, v236
	v_fma_f32 v232, v36, v237, v232
	v_fma_f32 v236, v37, v233, v236
	v_cvt_pk_bf16_f32 v131, v207, v211
	v_cvt_pk_bf16_f32 v139, v232, v236
	ds_write2_b32 v193, v128, v131 offset0:0 offset1:68
	ds_write2_b32 v254, v139, v136 offset0:136 offset1:204
	v_fma_f32 v208, v150, v207, v208
	v_fma_f32 v212, v150, v211, v212
	v_fma_f32 v208, v16, v211, v208
	v_fma_f32 v212, v17, v207, v212
	v_fma_f32 v231, v152, v232, v231
	v_fma_f32 v235, v152, v236, v235
	v_fma_f32 v231, v36, v236, v231
	v_fma_f32 v235, v37, v232, v235
	v_cvt_pk_bf16_f32 v132, v208, v212
	v_cvt_pk_bf16_f32 v143, v231, v235
	v_fma_f32 v209, v150, v208, v209
	v_fma_f32 v213, v150, v212, v213
	v_fma_f32 v209, v16, v212, v209
	v_fma_f32 v213, v17, v208, v213
	v_fma_f32 v230, v152, v231, v230
	v_fma_f32 v234, v152, v235, v234
	v_fma_f32 v230, v36, v235, v230
	v_fma_f32 v234, v37, v231, v234
	v_cvt_pk_bf16_f32 v135, v209, v213
	v_cvt_pk_bf16_f32 v187, v230, v234
	ds_write2_b32 v193, v132, v135 offset0:136 offset1:204
	ds_write2_b32 v254, v187, v143 offset0:0 offset1:68
	v_fma_f32 v214, v150, v209, v214
	v_fma_f32 v218, v150, v213, v218
	v_fma_f32 v214, v16, v213, v214
	v_fma_f32 v218, v17, v209, v218
	v_fma_f32 v225, v152, v230, v225
	v_fma_f32 v229, v152, v234, v229
	v_fma_f32 v225, v36, v234, v225
	v_fma_f32 v229, v37, v230, v229
	v_cvt_pk_bf16_f32 v128, v214, v218
	v_cvt_pk_bf16_f32 v136, v225, v229
; #define LAS __attribute__((address_space(3)))
; __device__ __forceinline__ unsigned pk2(float lo, float hi) { f32x2 v = {lo, hi}; nbf2 r = __builtin_convertvector(v, nbf2); return __builtin_bit_cast(unsigned, r); }
; #define WAVE_LDS_FENCE() asm volatile("s_waitcnt lgkmcnt(0)" ::: "memory")
; __device__ __forceinline__ float bf_at(const u32x4& lo, const u32x4& hi, int r) { const unsigned w = (r < 8 ? lo : hi)[(r & 7) >> 1]; return (r & 1) ? bf_hi(w) : bf_lo(w); }
; __device__ __forceinline__ void s5_out_phase(LAS unsigned char* lds, const bf16_t* UZ, const unsigned char* ws, const float* dskip, bf16_t* YG) {
;     ...
; #pragma unroll
;             for (int rr = 0; rr < 16; ++rr) {
;                 const int r = rr, rb = 15 - rr;
;                 { const f32x2 bb = {bf_at(fre0, fre1, r), bf_at(fim0, fim1, r)};
;                   const f32x2 n2 = cmac((f32x2){xfr, xfi}, (f32x2){ap[0].x, ap[0].x}, (f32x2){-ap[0].y, ap[0].y}, bb); xfr = n2.x; xfi = n2.y;
;                   *(LAS unsigned*)(xf + r * XB_PITCH + lane * 4) = pk2(n2.x, n2.y); }
;                 { const f32x2 bb = {bf_at(bre0, bre1, rb), bf_at(bim0, bim1, rb)};
;                   const f32x2 n2 = cmac((f32x2){xbr, xbi}, (f32x2){ap[1].x, ap[1].x}, (f32x2){-ap[1].y, ap[1].y}, bb); xbr = n2.x; xbi = n2.y;
;                   *(LAS unsigned*)(xbk + rb * XB_PITCH + lane * 4) = pk2(n2.x, n2.y); }
;             }
;             WAVE_LDS_FENCE();
; #pragma unroll
;             for (int ks = 0; ks < 4; ++ks) {
;                 const bf16x8 Xf = *(const LAS bf16x8*)(xf + fr * XB_PITCH + (8 * fq + 32 * ks) * 2);
;                 const bf16x8 Xb = *(const LAS bf16x8*)(xbk + fr * XB_PITCH + (8 * fq + 32 * ks) * 2);
;                 accY[mf] = __builtin_amdgcn_mfma_f32_16x16x32_bf16(Cf[0][ks], Xf, accY[mf], 0, 0, 0);
;                 accY[mb] = __builtin_amdgcn_mfma_f32_16x16x32_bf16(Cf[1][ks], Xb, accY[mb], 0, 0, 0);
;             }
	v_add_u32_e32 v193, 0x34c0, v103
	v_add_u32_e32 v254, 0x3900, v103
	v_fma_f32 v215, v150, v214, v215
	v_fma_f32 v219, v150, v218, v219
	v_fma_f32 v215, v16, v218, v215
	v_fma_f32 v219, v17, v214, v219
	v_fma_f32 v224, v152, v225, v224
	v_fma_f32 v228, v152, v229, v228
	v_fma_f32 v224, v36, v229, v224
	v_fma_f32 v228, v37, v225, v228
	v_cvt_pk_bf16_f32 v131, v215, v219
	v_cvt_pk_bf16_f32 v139, v224, v228
	ds_write2_b32 v193, v128, v131 offset0:0 offset1:68
	ds_write2_b32 v254, v139, v136 offset0:136 offset1:204
	v_fma_f32 v216, v150, v215, v216
	v_fma_f32 v220, v150, v219, v220
	v_fma_f32 v216, v16, v219, v216
	v_fma_f32 v220, v17, v215, v220
	v_fma_f32 v223, v152, v224, v223
	v_fma_f32 v227, v152, v228, v227
	v_fma_f32 v223, v36, v228, v223
	v_fma_f32 v227, v37, v224, v227
	v_cvt_pk_bf16_f32 v132, v216, v220
	v_cvt_pk_bf16_f32 v143, v223, v227
	v_fma_f32 v217, v150, v216, v217
	v_fma_f32 v221, v150, v220, v221
	v_fma_f32 v217, v16, v220, v217
	v_fma_f32 v221, v17, v216, v221
	v_fma_f32 v222, v152, v223, v222
	v_fma_f32 v226, v152, v227, v226
	v_fma_f32 v222, v36, v227, v222
	v_fma_f32 v226, v37, v223, v226
	v_cvt_pk_bf16_f32 v135, v217, v221
	v_cvt_pk_bf16_f32 v187, v222, v226
	ds_write2_b32 v193, v132, v135 offset0:136 offset1:204
	ds_write2_b32 v254, v187, v143 offset0:0 offset1:68
	v_mov_b32_e32 v114, v217
	v_mov_b32_e32 v119, v221
	v_mov_b32_e32 v121, v222
	v_mov_b32_e32 v127, v226
	ds_read_b128 v[188:191], v110 offset:10240
	ds_read_b128 v[194:197], v110 offset:10304
	ds_read_b128 v[198:201], v110 offset:10368
	ds_read_b128 v[202:205], v110 offset:10432
	ds_read_b128 v[206:209], v110 offset:14592
	ds_read_b128 v[210:213], v110 offset:14656
	ds_read_b128 v[214:217], v110 offset:14720
	ds_read_b128 v[218:221], v110 offset:14784
	s_waitcnt lgkmcnt(7)
	v_mfma_f32_16x16x32_bf16 v[56:59], v[0:3], v[188:191], 0
	s_waitcnt lgkmcnt(3)
	v_mfma_f32_16x16x32_bf16 v[52:55], v[20:23], v[206:209], 0
	v_mfma_f32_16x16x32_bf16 v[56:59], v[4:7], v[194:197], v[56:59]
	s_waitcnt lgkmcnt(2)
	v_mfma_f32_16x16x32_bf16 v[52:55], v[24:27], v[210:213], v[52:55]
	v_mfma_f32_16x16x32_bf16 v[56:59], v[8:11], v[198:201], v[56:59]
	s_waitcnt lgkmcnt(1)
	v_mfma_f32_16x16x32_bf16 v[52:55], v[28:31], v[214:217], v[52:55]
	v_mfma_f32_16x16x32_bf16 v[56:59], v[12:15], v[202:205], v[56:59]
	s_waitcnt lgkmcnt(0)
	v_mfma_f32_16x16x32_bf16 v[52:55], v[32:35], v[218:221], v[52:55]
	v_mfma_f32_4x4x4_16b_bf16 v[188:191], v[168:169], v[60:61], 0 cbsz:4 abid:0
	v_mfma_f32_4x4x4_16b_bf16 v[194:197], v[168:169], v[68:69], 0 cbsz:4 abid:0
	v_mfma_f32_4x4x4_16b_bf16 v[198:201], v[168:169], v[60:61], 0 cbsz:4 abid:1
	v_mfma_f32_4x4x4_16b_bf16 v[202:205], v[168:169], v[68:69], 0 cbsz:4 abid:1
	v_mfma_f32_4x4x4_16b_bf16 v[206:209], v[168:169], v[60:61], 0 cbsz:4 abid:2
	v_mfma_f32_4x4x4_16b_bf16 v[210:213], v[168:169], v[68:69], 0 cbsz:4 abid:2
	v_mfma_f32_4x4x4_16b_bf16 v[214:217], v[168:169], v[60:61], 0 cbsz:4 abid:3
	v_mfma_f32_4x4x4_16b_bf16 v[218:221], v[168:169], v[68:69], 0 cbsz:4 abid:3
	v_mfma_f32_4x4x4_16b_bf16 v[222:225], v[170:171], v[76:77], 0 cbsz:4 abid:0
	v_mfma_f32_4x4x4_16b_bf16 v[226:229], v[170:171], v[84:85], 0 cbsz:4 abid:0
	v_mfma_f32_4x4x4_16b_bf16 v[230:233], v[170:171], v[76:77], 0 cbsz:4 abid:1
	v_mfma_f32_4x4x4_16b_bf16 v[234:237], v[170:171], v[84:85], 0 cbsz:4 abid:1
	v_mfma_f32_4x4x4_16b_bf16 v[238:241], v[170:171], v[76:77], 0 cbsz:4 abid:2
	v_mfma_f32_4x4x4_16b_bf16 v[242:245], v[170:171], v[84:85], 0 cbsz:4 abid:2
	v_mfma_f32_4x4x4_16b_bf16 v[246:249], v[170:171], v[76:77], 0 cbsz:4 abid:3
	v_mfma_f32_4x4x4_16b_bf16 v[250:253], v[170:171], v[84:85], 0 cbsz:4 abid:3
	v_mfma_f32_4x4x4_16b_bf16 v[188:191], v[168:169], v[62:63], v[188:191] cbsz:4 abid:4
	v_mfma_f32_4x4x4_16b_bf16 v[194:197], v[168:169], v[70:71], v[194:197] cbsz:4 abid:4
	v_mfma_f32_4x4x4_16b_bf16 v[198:201], v[168:169], v[62:63], v[198:201] cbsz:4 abid:5
	v_mfma_f32_4x4x4_16b_bf16 v[202:205], v[168:169], v[70:71], v[202:205] cbsz:4 abid:5
	v_mfma_f32_4x4x4_16b_bf16 v[206:209], v[168:169], v[62:63], v[206:209] cbsz:4 abid:6
	v_mfma_f32_4x4x4_16b_bf16 v[210:213], v[168:169], v[70:71], v[210:213] cbsz:4 abid:6
	v_mfma_f32_4x4x4_16b_bf16 v[214:217], v[168:169], v[62:63], v[214:217] cbsz:4 abid:7
	v_mfma_f32_4x4x4_16b_bf16 v[218:221], v[168:169], v[70:71], v[218:221] cbsz:4 abid:7
	v_mfma_f32_4x4x4_16b_bf16 v[222:225], v[170:171], v[78:79], v[222:225] cbsz:4 abid:4
	v_mfma_f32_4x4x4_16b_bf16 v[226:229], v[170:171], v[86:87], v[226:229] cbsz:4 abid:4
	v_mfma_f32_4x4x4_16b_bf16 v[230:233], v[170:171], v[78:79], v[230:233] cbsz:4 abid:5
	v_mfma_f32_4x4x4_16b_bf16 v[234:237], v[170:171], v[86:87], v[234:237] cbsz:4 abid:5
	v_mfma_f32_4x4x4_16b_bf16 v[238:241], v[170:171], v[78:79], v[238:241] cbsz:4 abid:6
	v_mfma_f32_4x4x4_16b_bf16 v[242:245], v[170:171], v[86:87], v[242:245] cbsz:4 abid:6
	v_mfma_f32_4x4x4_16b_bf16 v[246:249], v[170:171], v[78:79], v[246:249] cbsz:4 abid:7
	v_mfma_f32_4x4x4_16b_bf16 v[250:253], v[170:171], v[86:87], v[250:253] cbsz:4 abid:7
	v_mfma_f32_4x4x4_16b_bf16 v[188:191], v[168:169], v[64:65], v[188:191] cbsz:4 abid:8
	v_mfma_f32_4x4x4_16b_bf16 v[194:197], v[168:169], v[72:73], v[194:197] cbsz:4 abid:8
	v_mfma_f32_4x4x4_16b_bf16 v[198:201], v[168:169], v[64:65], v[198:201] cbsz:4 abid:9
	v_mfma_f32_4x4x4_16b_bf16 v[202:205], v[168:169], v[72:73], v[202:205] cbsz:4 abid:9
	v_mfma_f32_4x4x4_16b_bf16 v[206:209], v[168:169], v[64:65], v[206:209] cbsz:4 abid:10
	v_mfma_f32_4x4x4_16b_bf16 v[210:213], v[168:169], v[72:73], v[210:213] cbsz:4 abid:10
	v_mfma_f32_4x4x4_16b_bf16 v[214:217], v[168:169], v[64:65], v[214:217] cbsz:4 abid:11
; #define LAS __attribute__((address_space(3)))
; __device__ __forceinline__ unsigned pk2(float lo, float hi) { f32x2 v = {lo, hi}; nbf2 r = __builtin_convertvector(v, nbf2); return __builtin_bit_cast(unsigned, r); }
; __device__ __forceinline__ void s5_out_phase(LAS unsigned char* lds, const bf16_t* UZ, const unsigned char* ws, const float* dskip, bf16_t* YG) {
;     ...
; #pragma unroll
;             for (int nt = 0; nt < 8; ++nt) {
;                 const f32x4 z = {0.f, 0.f, 0.f, 0.f};
;                 const f32x4 cf = __builtin_amdgcn_mfma_f32_16x16x16bf16_1k(Uf[mf], Bf[0][nt], z, 0, 0, 0);
;                 const f32x4 cb = __builtin_amdgcn_mfma_f32_16x16x16bf16_1k(Uf[mb], Bf[1][nt], z, 0, 0, 0);
;                 u32x2 wf, wb; wf.x = pk2(cf[0], cf[1]); wf.y = pk2(cf[2], cf[3]); wb.x = pk2(cb[0], cb[1]); wb.y = pk2(cb[2], cb[3]);
;                 *(LAS u32x2*)(wl + nt * 640 + wofs) = wf;
;                 *(LAS u32x2*)(wl + BUT_BYTES + nt * 640 + wofs) = wb;
;             }
;             WAVE_LDS_FENCE();
;             const LAS unsigned char* rp = wl + lane * 80;
;             const u32x4 fre0 = *(const LAS u32x4*)(rp), fre1 = *(const LAS u32x4*)(rp + 16), fim0 = *(const LAS u32x4*)(rp + 32), fim1 = *(const LAS u32x4*)(rp + 48);
;             const u32x4 bre0 = *(const LAS u32x4*)(rp + BUT_BYTES), bre1 = *(const LAS u32x4*)(rp + BUT_BYTES + 16), bim0 = *(const LAS u32x4*)(rp + BUT_BYTES + 32), bim1 = *(const LAS u32x4*)(rp + BUT_BYTES + 48);
;             LAS unsigned char* xf = wl + 2 * BUT_BYTES; LAS unsigned char* xbk = xf + XB_BYTES;
; #pragma unroll
;             for (int rr = 0; rr < 16; ++rr) {
;                 const int r = rr, rb = 15 - rr;
;                 { const f32x2 bb = {bf_at(fre0, fre1, r), bf_at(fim0, fim1, r)};
;                   const f32x2 n2 = cmac((f32x2){xfr, xfi}, (f32x2){ap[0].x, ap[0].x}, (f32x2){-ap[0].y, ap[0].y}, bb); xfr = n2.x; xfi = n2.y;
;                   *(LAS unsigned*)(xf + r * XB_PITCH + lane * 4) = pk2(n2.x, n2.y); }
;                 { const f32x2 bb = {bf_at(bre0, bre1, rb), bf_at(bim0, bim1, rb)};
;                   const f32x2 n2 = cmac((f32x2){xbr, xbi}, (f32x2){ap[1].x, ap[1].x}, (f32x2){-ap[1].y, ap[1].y}, bb); xbr = n2.x; xbi = n2.y;
;                   *(LAS unsigned*)(xbk + rb * XB_PITCH + lane * 4) = pk2(n2.x, n2.y); }
;             }
	v_mfma_f32_4x4x4_16b_bf16 v[218:221], v[168:169], v[72:73], v[218:221] cbsz:4 abid:11
	v_mfma_f32_4x4x4_16b_bf16 v[222:225], v[170:171], v[80:81], v[222:225] cbsz:4 abid:8
	v_mfma_f32_4x4x4_16b_bf16 v[226:229], v[170:171], v[88:89], v[226:229] cbsz:4 abid:8
	v_mfma_f32_4x4x4_16b_bf16 v[230:233], v[170:171], v[80:81], v[230:233] cbsz:4 abid:9
	v_mfma_f32_4x4x4_16b_bf16 v[234:237], v[170:171], v[88:89], v[234:237] cbsz:4 abid:9
	v_mfma_f32_4x4x4_16b_bf16 v[238:241], v[170:171], v[80:81], v[238:241] cbsz:4 abid:10
	v_mfma_f32_4x4x4_16b_bf16 v[242:245], v[170:171], v[88:89], v[242:245] cbsz:4 abid:10
	v_mfma_f32_4x4x4_16b_bf16 v[246:249], v[170:171], v[80:81], v[246:249] cbsz:4 abid:11
	v_mfma_f32_4x4x4_16b_bf16 v[250:253], v[170:171], v[88:89], v[250:253] cbsz:4 abid:11
	v_mfma_f32_4x4x4_16b_bf16 v[188:191], v[168:169], v[66:67], v[188:191] cbsz:4 abid:12
	v_mfma_f32_4x4x4_16b_bf16 v[194:197], v[168:169], v[74:75], v[194:197] cbsz:4 abid:12
	v_mfma_f32_4x4x4_16b_bf16 v[198:201], v[168:169], v[66:67], v[198:201] cbsz:4 abid:13
	v_mfma_f32_4x4x4_16b_bf16 v[202:205], v[168:169], v[74:75], v[202:205] cbsz:4 abid:13
	v_mfma_f32_4x4x4_16b_bf16 v[206:209], v[168:169], v[66:67], v[206:209] cbsz:4 abid:14
	v_mfma_f32_4x4x4_16b_bf16 v[210:213], v[168:169], v[74:75], v[210:213] cbsz:4 abid:14
	v_mfma_f32_4x4x4_16b_bf16 v[214:217], v[168:169], v[66:67], v[214:217] cbsz:4 abid:15
	v_mfma_f32_4x4x4_16b_bf16 v[218:221], v[168:169], v[74:75], v[218:221] cbsz:4 abid:15
	v_mfma_f32_4x4x4_16b_bf16 v[222:225], v[170:171], v[82:83], v[222:225] cbsz:4 abid:12
	v_mfma_f32_4x4x4_16b_bf16 v[226:229], v[170:171], v[90:91], v[226:229] cbsz:4 abid:12
	v_mfma_f32_4x4x4_16b_bf16 v[230:233], v[170:171], v[82:83], v[230:233] cbsz:4 abid:13
	v_mfma_f32_4x4x4_16b_bf16 v[234:237], v[170:171], v[90:91], v[234:237] cbsz:4 abid:13
	v_mfma_f32_4x4x4_16b_bf16 v[238:241], v[170:171], v[82:83], v[238:241] cbsz:4 abid:14
	v_mfma_f32_4x4x4_16b_bf16 v[242:245], v[170:171], v[90:91], v[242:245] cbsz:4 abid:14
	v_mfma_f32_4x4x4_16b_bf16 v[246:249], v[170:171], v[82:83], v[246:249] cbsz:4 abid:15
	v_mfma_f32_4x4x4_16b_bf16 v[250:253], v[170:171], v[90:91], v[250:253] cbsz:4 abid:15
	v_fma_f32 v188, v150, v114, v188
	v_fma_f32 v194, v150, v119, v194
	v_fma_f32 v188, v16, v119, v188
	v_fma_f32 v194, v17, v114, v194
	v_fma_f32 v249, v152, v121, v249
	v_fma_f32 v253, v152, v127, v253
	v_fma_f32 v249, v36, v127, v249
	v_fma_f32 v253, v37, v121, v253
	v_cvt_pk_bf16_f32 v128, v188, v194
	v_cvt_pk_bf16_f32 v136, v249, v253
	v_add_u32_e32 v193, 0x2800, v103
	v_add_u32_e32 v254, 0x45c0, v103
	v_fma_f32 v189, v150, v188, v189
	v_fma_f32 v195, v150, v194, v195
	v_fma_f32 v189, v16, v194, v189
	v_fma_f32 v195, v17, v188, v195
	v_fma_f32 v248, v152, v249, v248
	v_fma_f32 v252, v152, v253, v252
	v_fma_f32 v248, v36, v253, v248
	v_fma_f32 v252, v37, v249, v252
	v_cvt_pk_bf16_f32 v131, v189, v195
	v_cvt_pk_bf16_f32 v139, v248, v252
	ds_write2_b32 v193, v128, v131 offset0:0 offset1:68
	ds_write2_b32 v254, v139, v136 offset0:136 offset1:204
	v_fma_f32 v190, v150, v189, v190
	v_fma_f32 v196, v150, v195, v196
	v_fma_f32 v190, v16, v195, v190
	v_fma_f32 v196, v17, v189, v196
	v_fma_f32 v247, v152, v248, v247
	v_fma_f32 v251, v152, v252, v251
	v_fma_f32 v247, v36, v252, v247
	v_fma_f32 v251, v37, v248, v251
	v_cvt_pk_bf16_f32 v132, v190, v196
	v_cvt_pk_bf16_f32 v143, v247, v251
	v_fma_f32 v191, v150, v190, v191
	v_fma_f32 v197, v150, v196, v197
	v_fma_f32 v191, v16, v196, v191
	v_fma_f32 v197, v17, v190, v197
	v_fma_f32 v246, v152, v247, v246
	v_fma_f32 v250, v152, v251, v250
	v_fma_f32 v246, v36, v251, v246
	v_fma_f32 v250, v37, v247, v250
	v_cvt_pk_bf16_f32 v135, v191, v197
	v_cvt_pk_bf16_f32 v187, v246, v250
	ds_write2_b32 v193, v132, v135 offset0:136 offset1:204
	ds_write2_b32 v254, v187, v143 offset0:0 offset1:68
	v_fma_f32 v198, v150, v191, v198
	v_fma_f32 v202, v150, v197, v202
	v_fma_f32 v198, v16, v197, v198
	v_fma_f32 v202, v17, v191, v202
	v_fma_f32 v241, v152, v246, v241
	v_fma_f32 v245, v152, v250, v245
	v_fma_f32 v241, v36, v250, v241
	v_fma_f32 v245, v37, v246, v245
	v_cvt_pk_bf16_f32 v128, v198, v202
	v_cvt_pk_bf16_f32 v136, v241, v245
	v_add_u32_e32 v193, 0x2c40, v103
	v_add_u32_e32 v254, 0x4180, v103
	v_fma_f32 v199, v150, v198, v199
	v_fma_f32 v203, v150, v202, v203
	v_fma_f32 v199, v16, v202, v199
	v_fma_f32 v203, v17, v198, v203
	v_fma_f32 v240, v152, v241, v240
	v_fma_f32 v244, v152, v245, v244
	v_fma_f32 v240, v36, v245, v240
	v_fma_f32 v244, v37, v241, v244
	v_cvt_pk_bf16_f32 v131, v199, v203
	v_cvt_pk_bf16_f32 v139, v240, v244
	ds_write2_b32 v193, v128, v131 offset0:0 offset1:68
	ds_write2_b32 v254, v139, v136 offset0:136 offset1:204
	v_fma_f32 v200, v150, v199, v200
	v_fma_f32 v204, v150, v203, v204
	v_fma_f32 v200, v16, v203, v200
	v_fma_f32 v204, v17, v199, v204
	v_fma_f32 v239, v152, v240, v239
	v_fma_f32 v243, v152, v244, v243
	v_fma_f32 v239, v36, v244, v239
	v_fma_f32 v243, v37, v240, v243
	v_cvt_pk_bf16_f32 v132, v200, v204
	v_cvt_pk_bf16_f32 v143, v239, v243
	v_fma_f32 v201, v150, v200, v201
	v_fma_f32 v205, v150, v204, v205
	v_fma_f32 v201, v16, v204, v201
	v_fma_f32 v205, v17, v200, v205
	v_fma_f32 v238, v152, v239, v238
	v_fma_f32 v242, v152, v243, v242
	v_fma_f32 v238, v36, v243, v238
	v_fma_f32 v242, v37, v239, v242
	v_cvt_pk_bf16_f32 v135, v201, v205
	v_cvt_pk_bf16_f32 v187, v238, v242
	ds_write2_b32 v193, v132, v135 offset0:136 offset1:204
	ds_write2_b32 v254, v187, v143 offset0:0 offset1:68
	v_fma_f32 v206, v150, v201, v206
	v_fma_f32 v210, v150, v205, v210
	v_fma_f32 v206, v16, v205, v206
	v_fma_f32 v210, v17, v201, v210
	v_fma_f32 v233, v152, v238, v233
; #define LAS __attribute__((address_space(3)))
; __device__ __forceinline__ unsigned pk2(float lo, float hi) { f32x2 v = {lo, hi}; nbf2 r = __builtin_convertvector(v, nbf2); return __builtin_bit_cast(unsigned, r); }
; #define WAVE_LDS_FENCE() asm volatile("s_waitcnt lgkmcnt(0)" ::: "memory")
; __device__ __forceinline__ float bf_at(const u32x4& lo, const u32x4& hi, int r) { const unsigned w = (r < 8 ? lo : hi)[(r & 7) >> 1]; return (r & 1) ? bf_hi(w) : bf_lo(w); }
; __device__ __forceinline__ void s5_out_phase(LAS unsigned char* lds, const bf16_t* UZ, const unsigned char* ws, const float* dskip, bf16_t* YG) {
;     ...
; #pragma unroll
;             for (int nt = 0; nt < 8; ++nt) {
;                 const f32x4 z = {0.f, 0.f, 0.f, 0.f};
;                 const f32x4 cf = __builtin_amdgcn_mfma_f32_16x16x16bf16_1k(Uf[mf], Bf[0][nt], z, 0, 0, 0);
;                 const f32x4 cb = __builtin_amdgcn_mfma_f32_16x16x16bf16_1k(Uf[mb], Bf[1][nt], z, 0, 0, 0);
;     ...
; #pragma unroll
;             for (int rr = 0; rr < 16; ++rr) {
;                 const int r = rr, rb = 15 - rr;
;                 { const f32x2 bb = {bf_at(fre0, fre1, r), bf_at(fim0, fim1, r)};
;                   const f32x2 n2 = cmac((f32x2){xfr, xfi}, (f32x2){ap[0].x, ap[0].x}, (f32x2){-ap[0].y, ap[0].y}, bb); xfr = n2.x; xfi = n2.y;
;                   *(LAS unsigned*)(xf + r * XB_PITCH + lane * 4) = pk2(n2.x, n2.y); }
;                 { const f32x2 bb = {bf_at(bre0, bre1, rb), bf_at(bim0, bim1, rb)};
;                   const f32x2 n2 = cmac((f32x2){xbr, xbi}, (f32x2){ap[1].x, ap[1].x}, (f32x2){-ap[1].y, ap[1].y}, bb); xbr = n2.x; xbi = n2.y;
;                   *(LAS unsigned*)(xbk + rb * XB_PITCH + lane * 4) = pk2(n2.x, n2.y); }
;             }
;             WAVE_LDS_FENCE();
; #pragma unroll
;             for (int ks = 0; ks < 4; ++ks) {
;                 const bf16x8 Xf = *(const LAS bf16x8*)(xf + fr * XB_PITCH + (8 * fq + 32 * ks) * 2);
;                 const bf16x8 Xb = *(const LAS bf16x8*)(xbk + fr * XB_PITCH + (8 * fq + 32 * ks) * 2);
;                 accY[mf] = __builtin_amdgcn_mfma_f32_16x16x32_bf16(Cf[0][ks], Xf, accY[mf], 0, 0, 0);
;                 accY[mb] = __builtin_amdgcn_mfma_f32_16x16x32_bf16(Cf[1][ks], Xb, accY[mb], 0, 0, 0);
;             }
	v_fma_f32 v237, v152, v242, v237
	v_fma_f32 v233, v36, v242, v233
	v_fma_f32 v237, v37, v238, v237
	v_cvt_pk_bf16_f32 v128, v206, v210
	v_cvt_pk_bf16_f32 v136, v233, v237
	v_add_u32_e32 v193, 0x3080, v103
	v_add_u32_e32 v254, 0x3d40, v103
	v_fma_f32 v207, v150, v206, v207
	v_fma_f32 v211, v150, v210, v211
	v_fma_f32 v207, v16, v210, v207
	v_fma_f32 v211, v17, v206, v211
	v_fma_f32 v232, v152, v233, v232
	v_fma_f32 v236, v152, v237, v236
	v_fma_f32 v232, v36, v237, v232
	v_fma_f32 v236, v37, v233, v236
	v_cvt_pk_bf16_f32 v131, v207, v211
	v_cvt_pk_bf16_f32 v139, v232, v236
	ds_write2_b32 v193, v128, v131 offset0:0 offset1:68
	ds_write2_b32 v254, v139, v136 offset0:136 offset1:204
	v_fma_f32 v208, v150, v207, v208
	v_fma_f32 v212, v150, v211, v212
	v_fma_f32 v208, v16, v211, v208
	v_fma_f32 v212, v17, v207, v212
	v_fma_f32 v231, v152, v232, v231
	v_fma_f32 v235, v152, v236, v235
	v_fma_f32 v231, v36, v236, v231
	v_fma_f32 v235, v37, v232, v235
	v_cvt_pk_bf16_f32 v132, v208, v212
	v_cvt_pk_bf16_f32 v143, v231, v235
	v_fma_f32 v209, v150, v208, v209
	v_fma_f32 v213, v150, v212, v213
	v_fma_f32 v209, v16, v212, v209
	v_fma_f32 v213, v17, v208, v213
	v_fma_f32 v230, v152, v231, v230
	v_fma_f32 v234, v152, v235, v234
	v_fma_f32 v230, v36, v235, v230
	v_fma_f32 v234, v37, v231, v234
	v_cvt_pk_bf16_f32 v135, v209, v213
	v_cvt_pk_bf16_f32 v187, v230, v234
	ds_write2_b32 v193, v132, v135 offset0:136 offset1:204
	ds_write2_b32 v254, v187, v143 offset0:0 offset1:68
	v_fma_f32 v214, v150, v209, v214
	v_fma_f32 v218, v150, v213, v218
	v_fma_f32 v214, v16, v213, v214
	v_fma_f32 v218, v17, v209, v218
	v_fma_f32 v225, v152, v230, v225
	v_fma_f32 v229, v152, v234, v229
	v_fma_f32 v225, v36, v234, v225
	v_fma_f32 v229, v37, v230, v229
	v_cvt_pk_bf16_f32 v128, v214, v218
	v_cvt_pk_bf16_f32 v136, v225, v229
	v_add_u32_e32 v193, 0x34c0, v103
	v_add_u32_e32 v254, 0x3900, v103
	v_fma_f32 v215, v150, v214, v215
	v_fma_f32 v219, v150, v218, v219
	v_fma_f32 v215, v16, v218, v215
	v_fma_f32 v219, v17, v214, v219
	v_fma_f32 v224, v152, v225, v224
	v_fma_f32 v228, v152, v229, v228
	v_fma_f32 v224, v36, v229, v224
	v_fma_f32 v228, v37, v225, v228
	v_cvt_pk_bf16_f32 v131, v215, v219
	v_cvt_pk_bf16_f32 v139, v224, v228
	ds_write2_b32 v193, v128, v131 offset0:0 offset1:68
	ds_write2_b32 v254, v139, v136 offset0:136 offset1:204
	v_fma_f32 v216, v150, v215, v216
	v_fma_f32 v220, v150, v219, v220
	v_fma_f32 v216, v16, v219, v216
	v_fma_f32 v220, v17, v215, v220
	v_fma_f32 v223, v152, v224, v223
	v_fma_f32 v227, v152, v228, v227
	v_fma_f32 v223, v36, v228, v223
	v_fma_f32 v227, v37, v224, v227
	v_cvt_pk_bf16_f32 v132, v216, v220
	v_cvt_pk_bf16_f32 v143, v223, v227
	v_fma_f32 v217, v150, v216, v217
	v_fma_f32 v221, v150, v220, v221
	v_fma_f32 v217, v16, v220, v217
	v_fma_f32 v221, v17, v216, v221
	v_fma_f32 v222, v152, v223, v222
	v_fma_f32 v226, v152, v227, v226
	v_fma_f32 v222, v36, v227, v222
	v_fma_f32 v226, v37, v223, v226
	v_cvt_pk_bf16_f32 v135, v217, v221
	v_cvt_pk_bf16_f32 v187, v222, v226
	ds_write2_b32 v193, v132, v135 offset0:136 offset1:204
	ds_write2_b32 v254, v187, v143 offset0:0 offset1:68
	v_mov_b32_e32 v114, v217
	v_mov_b32_e32 v119, v221
	v_mov_b32_e32 v121, v222
	v_mov_b32_e32 v127, v226
	ds_read_b128 v[188:191], v110 offset:10240
	ds_read_b128 v[194:197], v110 offset:10304
	ds_read_b128 v[198:201], v110 offset:10368
	ds_read_b128 v[202:205], v110 offset:10432
	ds_read_b128 v[206:209], v110 offset:14592
	ds_read_b128 v[210:213], v110 offset:14656
	ds_read_b128 v[214:217], v110 offset:14720
	ds_read_b128 v[218:221], v110 offset:14784
	s_waitcnt lgkmcnt(7)
	v_mfma_f32_16x16x32_bf16 v[52:55], v[0:3], v[188:191], v[52:55]
	s_waitcnt lgkmcnt(3)
	v_mfma_f32_16x16x32_bf16 v[56:59], v[20:23], v[206:209], v[56:59]
	v_mfma_f32_16x16x32_bf16 v[52:55], v[4:7], v[194:197], v[52:55]
	s_waitcnt lgkmcnt(2)
	v_mfma_f32_16x16x32_bf16 v[56:59], v[24:27], v[210:213], v[56:59]
	v_mfma_f32_16x16x32_bf16 v[52:55], v[8:11], v[198:201], v[52:55]
	s_waitcnt lgkmcnt(1)
	v_mfma_f32_16x16x32_bf16 v[56:59], v[28:31], v[214:217], v[56:59]
	v_mfma_f32_16x16x32_bf16 v[52:55], v[12:15], v[202:205], v[52:55]
	s_waitcnt lgkmcnt(0)
	v_mfma_f32_16x16x32_bf16 v[56:59], v[32:35], v[218:221], v[56:59]
	v_mfma_f32_4x4x4_16b_bf16 v[188:191], v[116:117], v[60:61], 0 cbsz:4 abid:0
	v_mfma_f32_4x4x4_16b_bf16 v[194:197], v[116:117], v[68:69], 0 cbsz:4 abid:0
	v_mfma_f32_4x4x4_16b_bf16 v[198:201], v[116:117], v[60:61], 0 cbsz:4 abid:1
	v_mfma_f32_4x4x4_16b_bf16 v[202:205], v[116:117], v[68:69], 0 cbsz:4 abid:1
	v_mfma_f32_4x4x4_16b_bf16 v[206:209], v[116:117], v[60:61], 0 cbsz:4 abid:2
	v_mfma_f32_4x4x4_16b_bf16 v[210:213], v[116:117], v[68:69], 0 cbsz:4 abid:2
	v_mfma_f32_4x4x4_16b_bf16 v[214:217], v[116:117], v[60:61], 0 cbsz:4 abid:3
	v_mfma_f32_4x4x4_16b_bf16 v[218:221], v[116:117], v[68:69], 0 cbsz:4 abid:3
	v_mfma_f32_4x4x4_16b_bf16 v[222:225], v[172:173], v[76:77], 0 cbsz:4 abid:0
	v_mfma_f32_4x4x4_16b_bf16 v[226:229], v[172:173], v[84:85], 0 cbsz:4 abid:0
	v_mfma_f32_4x4x4_16b_bf16 v[230:233], v[172:173], v[76:77], 0 cbsz:4 abid:1
	v_mfma_f32_4x4x4_16b_bf16 v[234:237], v[172:173], v[84:85], 0 cbsz:4 abid:1
	v_mfma_f32_4x4x4_16b_bf16 v[238:241], v[172:173], v[76:77], 0 cbsz:4 abid:2
	v_mfma_f32_4x4x4_16b_bf16 v[242:245], v[172:173], v[84:85], 0 cbsz:4 abid:2
	v_mfma_f32_4x4x4_16b_bf16 v[246:249], v[172:173], v[76:77], 0 cbsz:4 abid:3
	v_mfma_f32_4x4x4_16b_bf16 v[250:253], v[172:173], v[84:85], 0 cbsz:4 abid:3
	v_mfma_f32_4x4x4_16b_bf16 v[188:191], v[116:117], v[62:63], v[188:191] cbsz:4 abid:4
	v_mfma_f32_4x4x4_16b_bf16 v[194:197], v[116:117], v[70:71], v[194:197] cbsz:4 abid:4
; #define LAS __attribute__((address_space(3)))
; __device__ __forceinline__ unsigned pk2(float lo, float hi) { f32x2 v = {lo, hi}; nbf2 r = __builtin_convertvector(v, nbf2); return __builtin_bit_cast(unsigned, r); }
; __device__ __forceinline__ void s5_out_phase(LAS unsigned char* lds, const bf16_t* UZ, const unsigned char* ws, const float* dskip, bf16_t* YG) {
;     ...
; #pragma unroll
;             for (int nt = 0; nt < 8; ++nt) {
;                 const f32x4 z = {0.f, 0.f, 0.f, 0.f};
;                 const f32x4 cf = __builtin_amdgcn_mfma_f32_16x16x16bf16_1k(Uf[mf], Bf[0][nt], z, 0, 0, 0);
;                 const f32x4 cb = __builtin_amdgcn_mfma_f32_16x16x16bf16_1k(Uf[mb], Bf[1][nt], z, 0, 0, 0);
;                 u32x2 wf, wb; wf.x = pk2(cf[0], cf[1]); wf.y = pk2(cf[2], cf[3]); wb.x = pk2(cb[0], cb[1]); wb.y = pk2(cb[2], cb[3]);
;                 *(LAS u32x2*)(wl + nt * 640 + wofs) = wf;
;                 *(LAS u32x2*)(wl + BUT_BYTES + nt * 640 + wofs) = wb;
;             }
;             WAVE_LDS_FENCE();
;             const LAS unsigned char* rp = wl + lane * 80;
;             const u32x4 fre0 = *(const LAS u32x4*)(rp), fre1 = *(const LAS u32x4*)(rp + 16), fim0 = *(const LAS u32x4*)(rp + 32), fim1 = *(const LAS u32x4*)(rp + 48);
;             const u32x4 bre0 = *(const LAS u32x4*)(rp + BUT_BYTES), bre1 = *(const LAS u32x4*)(rp + BUT_BYTES + 16), bim0 = *(const LAS u32x4*)(rp + BUT_BYTES + 32), bim1 = *(const LAS u32x4*)(rp + BUT_BYTES + 48);
;             LAS unsigned char* xf = wl + 2 * BUT_BYTES; LAS unsigned char* xbk = xf + XB_BYTES;
; #pragma unroll
;             for (int rr = 0; rr < 16; ++rr) {
;                 const int r = rr, rb = 15 - rr;
;                 { const f32x2 bb = {bf_at(fre0, fre1, r), bf_at(fim0, fim1, r)};
;                   const f32x2 n2 = cmac((f32x2){xfr, xfi}, (f32x2){ap[0].x, ap[0].x}, (f32x2){-ap[0].y, ap[0].y}, bb); xfr = n2.x; xfi = n2.y;
;                   *(LAS unsigned*)(xf + r * XB_PITCH + lane * 4) = pk2(n2.x, n2.y); }
;                 { const f32x2 bb = {bf_at(bre0, bre1, rb), bf_at(bim0, bim1, rb)};
;                   const f32x2 n2 = cmac((f32x2){xbr, xbi}, (f32x2){ap[1].x, ap[1].x}, (f32x2){-ap[1].y, ap[1].y}, bb); xbr = n2.x; xbi = n2.y;
;                   *(LAS unsigned*)(xbk + rb * XB_PITCH + lane * 4) = pk2(n2.x, n2.y); }
;             }
	v_mfma_f32_4x4x4_16b_bf16 v[198:201], v[116:117], v[62:63], v[198:201] cbsz:4 abid:5
	v_mfma_f32_4x4x4_16b_bf16 v[202:205], v[116:117], v[70:71], v[202:205] cbsz:4 abid:5
	v_mfma_f32_4x4x4_16b_bf16 v[206:209], v[116:117], v[62:63], v[206:209] cbsz:4 abid:6
	v_mfma_f32_4x4x4_16b_bf16 v[210:213], v[116:117], v[70:71], v[210:213] cbsz:4 abid:6
	v_mfma_f32_4x4x4_16b_bf16 v[214:217], v[116:117], v[62:63], v[214:217] cbsz:4 abid:7
	v_mfma_f32_4x4x4_16b_bf16 v[218:221], v[116:117], v[70:71], v[218:221] cbsz:4 abid:7
	v_mfma_f32_4x4x4_16b_bf16 v[222:225], v[172:173], v[78:79], v[222:225] cbsz:4 abid:4
	v_mfma_f32_4x4x4_16b_bf16 v[226:229], v[172:173], v[86:87], v[226:229] cbsz:4 abid:4
	v_mfma_f32_4x4x4_16b_bf16 v[230:233], v[172:173], v[78:79], v[230:233] cbsz:4 abid:5
	v_mfma_f32_4x4x4_16b_bf16 v[234:237], v[172:173], v[86:87], v[234:237] cbsz:4 abid:5
	v_mfma_f32_4x4x4_16b_bf16 v[238:241], v[172:173], v[78:79], v[238:241] cbsz:4 abid:6
	v_mfma_f32_4x4x4_16b_bf16 v[242:245], v[172:173], v[86:87], v[242:245] cbsz:4 abid:6
	v_mfma_f32_4x4x4_16b_bf16 v[246:249], v[172:173], v[78:79], v[246:249] cbsz:4 abid:7
	v_mfma_f32_4x4x4_16b_bf16 v[250:253], v[172:173], v[86:87], v[250:253] cbsz:4 abid:7
	v_mfma_f32_4x4x4_16b_bf16 v[188:191], v[116:117], v[64:65], v[188:191] cbsz:4 abid:8
	v_mfma_f32_4x4x4_16b_bf16 v[194:197], v[116:117], v[72:73], v[194:197] cbsz:4 abid:8
	v_mfma_f32_4x4x4_16b_bf16 v[198:201], v[116:117], v[64:65], v[198:201] cbsz:4 abid:9
	v_mfma_f32_4x4x4_16b_bf16 v[202:205], v[116:117], v[72:73], v[202:205] cbsz:4 abid:9
	v_mfma_f32_4x4x4_16b_bf16 v[206:209], v[116:117], v[64:65], v[206:209] cbsz:4 abid:10
	v_mfma_f32_4x4x4_16b_bf16 v[210:213], v[116:117], v[72:73], v[210:213] cbsz:4 abid:10
	v_mfma_f32_4x4x4_16b_bf16 v[214:217], v[116:117], v[64:65], v[214:217] cbsz:4 abid:11
	v_mfma_f32_4x4x4_16b_bf16 v[218:221], v[116:117], v[72:73], v[218:221] cbsz:4 abid:11
	v_mfma_f32_4x4x4_16b_bf16 v[222:225], v[172:173], v[80:81], v[222:225] cbsz:4 abid:8
	v_mfma_f32_4x4x4_16b_bf16 v[226:229], v[172:173], v[88:89], v[226:229] cbsz:4 abid:8
	v_mfma_f32_4x4x4_16b_bf16 v[230:233], v[172:173], v[80:81], v[230:233] cbsz:4 abid:9
	v_mfma_f32_4x4x4_16b_bf16 v[234:237], v[172:173], v[88:89], v[234:237] cbsz:4 abid:9
	v_mfma_f32_4x4x4_16b_bf16 v[238:241], v[172:173], v[80:81], v[238:241] cbsz:4 abid:10
	v_mfma_f32_4x4x4_16b_bf16 v[242:245], v[172:173], v[88:89], v[242:245] cbsz:4 abid:10
	v_mfma_f32_4x4x4_16b_bf16 v[246:249], v[172:173], v[80:81], v[246:249] cbsz:4 abid:11
	v_mfma_f32_4x4x4_16b_bf16 v[250:253], v[172:173], v[88:89], v[250:253] cbsz:4 abid:11
	v_mfma_f32_4x4x4_16b_bf16 v[188:191], v[116:117], v[66:67], v[188:191] cbsz:4 abid:12
	v_mfma_f32_4x4x4_16b_bf16 v[194:197], v[116:117], v[74:75], v[194:197] cbsz:4 abid:12
	v_mfma_f32_4x4x4_16b_bf16 v[198:201], v[116:117], v[66:67], v[198:201] cbsz:4 abid:13
	v_mfma_f32_4x4x4_16b_bf16 v[202:205], v[116:117], v[74:75], v[202:205] cbsz:4 abid:13
	v_mfma_f32_4x4x4_16b_bf16 v[206:209], v[116:117], v[66:67], v[206:209] cbsz:4 abid:14
	v_mfma_f32_4x4x4_16b_bf16 v[210:213], v[116:117], v[74:75], v[210:213] cbsz:4 abid:14
	v_mfma_f32_4x4x4_16b_bf16 v[214:217], v[116:117], v[66:67], v[214:217] cbsz:4 abid:15
	v_mfma_f32_4x4x4_16b_bf16 v[218:221], v[116:117], v[74:75], v[218:221] cbsz:4 abid:15
	v_mfma_f32_4x4x4_16b_bf16 v[222:225], v[172:173], v[82:83], v[222:225] cbsz:4 abid:12
	v_mfma_f32_4x4x4_16b_bf16 v[226:229], v[172:173], v[90:91], v[226:229] cbsz:4 abid:12
	v_mfma_f32_4x4x4_16b_bf16 v[230:233], v[172:173], v[82:83], v[230:233] cbsz:4 abid:13
	v_mfma_f32_4x4x4_16b_bf16 v[234:237], v[172:173], v[90:91], v[234:237] cbsz:4 abid:13
	v_mfma_f32_4x4x4_16b_bf16 v[238:241], v[172:173], v[82:83], v[238:241] cbsz:4 abid:14
	v_mfma_f32_4x4x4_16b_bf16 v[242:245], v[172:173], v[90:91], v[242:245] cbsz:4 abid:14
	v_mfma_f32_4x4x4_16b_bf16 v[246:249], v[172:173], v[82:83], v[246:249] cbsz:4 abid:15
	v_mfma_f32_4x4x4_16b_bf16 v[250:253], v[172:173], v[90:91], v[250:253] cbsz:4 abid:15
	v_fma_f32 v188, v150, v114, v188
	v_fma_f32 v194, v150, v119, v194
	v_fma_f32 v188, v16, v119, v188
	v_fma_f32 v194, v17, v114, v194
	v_fma_f32 v249, v152, v121, v249
	v_fma_f32 v253, v152, v127, v253
	v_fma_f32 v249, v36, v127, v249
	v_fma_f32 v253, v37, v121, v253
	v_cvt_pk_bf16_f32 v128, v188, v194
	v_cvt_pk_bf16_f32 v136, v249, v253
	v_add_u32_e32 v193, 0x2800, v103
	v_add_u32_e32 v254, 0x45c0, v103
	v_fma_f32 v189, v150, v188, v189
	v_fma_f32 v195, v150, v194, v195
	v_fma_f32 v189, v16, v194, v189
	v_fma_f32 v195, v17, v188, v195
	v_fma_f32 v248, v152, v249, v248
	v_fma_f32 v252, v152, v253, v252
	v_fma_f32 v248, v36, v253, v248
	v_fma_f32 v252, v37, v249, v252
	v_cvt_pk_bf16_f32 v131, v189, v195
	v_cvt_pk_bf16_f32 v139, v248, v252
	ds_write2_b32 v193, v128, v131 offset0:0 offset1:68
	ds_write2_b32 v254, v139, v136 offset0:136 offset1:204
	v_fma_f32 v190, v150, v189, v190
	v_fma_f32 v196, v150, v195, v196
	v_fma_f32 v190, v16, v195, v190
	v_fma_f32 v196, v17, v189, v196
	v_fma_f32 v247, v152, v248, v247
	v_fma_f32 v251, v152, v252, v251
	v_fma_f32 v247, v36, v252, v247
	v_fma_f32 v251, v37, v248, v251
	v_cvt_pk_bf16_f32 v132, v190, v196
	v_cvt_pk_bf16_f32 v143, v247, v251
	v_fma_f32 v191, v150, v190, v191
	v_fma_f32 v197, v150, v196, v197
	v_fma_f32 v191, v16, v196, v191
	v_fma_f32 v197, v17, v190, v197
	v_fma_f32 v246, v152, v247, v246
	v_fma_f32 v250, v152, v251, v250
	v_fma_f32 v246, v36, v251, v246
	v_fma_f32 v250, v37, v247, v250
	v_cvt_pk_bf16_f32 v135, v191, v197
	v_cvt_pk_bf16_f32 v187, v246, v250
	ds_write2_b32 v193, v132, v135 offset0:136 offset1:204
	ds_write2_b32 v254, v187, v143 offset0:0 offset1:68
; #define LAS __attribute__((address_space(3)))
; __device__ __forceinline__ unsigned pk2(float lo, float hi) { f32x2 v = {lo, hi}; nbf2 r = __builtin_convertvector(v, nbf2); return __builtin_bit_cast(unsigned, r); }
; #define WAVE_LDS_FENCE() asm volatile("s_waitcnt lgkmcnt(0)" ::: "memory")
; __device__ __forceinline__ float bf_at(const u32x4& lo, const u32x4& hi, int r) { const unsigned w = (r < 8 ? lo : hi)[(r & 7) >> 1]; return (r & 1) ? bf_hi(w) : bf_lo(w); }
; __device__ __forceinline__ void s5_out_phase(LAS unsigned char* lds, const bf16_t* UZ, const unsigned char* ws, const float* dskip, bf16_t* YG) {
;     ...
; #pragma unroll
;             for (int rr = 0; rr < 16; ++rr) {
;                 const int r = rr, rb = 15 - rr;
;                 { const f32x2 bb = {bf_at(fre0, fre1, r), bf_at(fim0, fim1, r)};
;                   const f32x2 n2 = cmac((f32x2){xfr, xfi}, (f32x2){ap[0].x, ap[0].x}, (f32x2){-ap[0].y, ap[0].y}, bb); xfr = n2.x; xfi = n2.y;
;                   *(LAS unsigned*)(xf + r * XB_PITCH + lane * 4) = pk2(n2.x, n2.y); }
;                 { const f32x2 bb = {bf_at(bre0, bre1, rb), bf_at(bim0, bim1, rb)};
;                   const f32x2 n2 = cmac((f32x2){xbr, xbi}, (f32x2){ap[1].x, ap[1].x}, (f32x2){-ap[1].y, ap[1].y}, bb); xbr = n2.x; xbi = n2.y;
;                   *(LAS unsigned*)(xbk + rb * XB_PITCH + lane * 4) = pk2(n2.x, n2.y); }
;             }
;             WAVE_LDS_FENCE();
; #pragma unroll
;             for (int ks = 0; ks < 4; ++ks) {
;                 const bf16x8 Xf = *(const LAS bf16x8*)(xf + fr * XB_PITCH + (8 * fq + 32 * ks) * 2);
;                 const bf16x8 Xb = *(const LAS bf16x8*)(xbk + fr * XB_PITCH + (8 * fq + 32 * ks) * 2);
;                 accY[mf] = __builtin_amdgcn_mfma_f32_16x16x32_bf16(Cf[0][ks], Xf, accY[mf], 0, 0, 0);
;                 accY[mb] = __builtin_amdgcn_mfma_f32_16x16x32_bf16(Cf[1][ks], Xb, accY[mb], 0, 0, 0);
;             }
	v_fma_f32 v198, v150, v191, v198
	v_fma_f32 v202, v150, v197, v202
	v_fma_f32 v198, v16, v197, v198
	v_fma_f32 v202, v17, v191, v202
	v_fma_f32 v241, v152, v246, v241
	v_fma_f32 v245, v152, v250, v245
	v_fma_f32 v241, v36, v250, v241
	v_fma_f32 v245, v37, v246, v245
	v_cvt_pk_bf16_f32 v128, v198, v202
	v_cvt_pk_bf16_f32 v136, v241, v245
	v_add_u32_e32 v193, 0x2c40, v103
	v_add_u32_e32 v254, 0x4180, v103
	v_fma_f32 v199, v150, v198, v199
	v_fma_f32 v203, v150, v202, v203
	v_fma_f32 v199, v16, v202, v199
	v_fma_f32 v203, v17, v198, v203
	v_fma_f32 v240, v152, v241, v240
	v_fma_f32 v244, v152, v245, v244
	v_fma_f32 v240, v36, v245, v240
	v_fma_f32 v244, v37, v241, v244
	v_cvt_pk_bf16_f32 v131, v199, v203
	v_cvt_pk_bf16_f32 v139, v240, v244
	ds_write2_b32 v193, v128, v131 offset0:0 offset1:68
	ds_write2_b32 v254, v139, v136 offset0:136 offset1:204
	v_fma_f32 v200, v150, v199, v200
	v_fma_f32 v204, v150, v203, v204
	v_fma_f32 v200, v16, v203, v200
	v_fma_f32 v204, v17, v199, v204
	v_fma_f32 v239, v152, v240, v239
	v_fma_f32 v243, v152, v244, v243
	v_fma_f32 v239, v36, v244, v239
	v_fma_f32 v243, v37, v240, v243
	v_cvt_pk_bf16_f32 v132, v200, v204
	v_cvt_pk_bf16_f32 v143, v239, v243
	v_fma_f32 v201, v150, v200, v201
	v_fma_f32 v205, v150, v204, v205
	v_fma_f32 v201, v16, v204, v201
	v_fma_f32 v205, v17, v200, v205
	v_fma_f32 v238, v152, v239, v238
	v_fma_f32 v242, v152, v243, v242
	v_fma_f32 v238, v36, v243, v238
	v_fma_f32 v242, v37, v239, v242
	v_cvt_pk_bf16_f32 v135, v201, v205
	v_cvt_pk_bf16_f32 v187, v238, v242
	ds_write2_b32 v193, v132, v135 offset0:136 offset1:204
	ds_write2_b32 v254, v187, v143 offset0:0 offset1:68
	v_fma_f32 v206, v150, v201, v206
	v_fma_f32 v210, v150, v205, v210
	v_fma_f32 v206, v16, v205, v206
	v_fma_f32 v210, v17, v201, v210
	v_fma_f32 v233, v152, v238, v233
	v_fma_f32 v237, v152, v242, v237
	v_fma_f32 v233, v36, v242, v233
	v_fma_f32 v237, v37, v238, v237
	v_cvt_pk_bf16_f32 v128, v206, v210
	v_cvt_pk_bf16_f32 v136, v233, v237
	v_add_u32_e32 v193, 0x3080, v103
	v_add_u32_e32 v254, 0x3d40, v103
	v_fma_f32 v207, v150, v206, v207
	v_fma_f32 v211, v150, v210, v211
	v_fma_f32 v207, v16, v210, v207
	v_fma_f32 v211, v17, v206, v211
	v_fma_f32 v232, v152, v233, v232
	v_fma_f32 v236, v152, v237, v236
	v_fma_f32 v232, v36, v237, v232
	v_fma_f32 v236, v37, v233, v236
	v_cvt_pk_bf16_f32 v131, v207, v211
	v_cvt_pk_bf16_f32 v139, v232, v236
	ds_write2_b32 v193, v128, v131 offset0:0 offset1:68
	ds_write2_b32 v254, v139, v136 offset0:136 offset1:204
	v_fma_f32 v208, v150, v207, v208
	v_fma_f32 v212, v150, v211, v212
	v_fma_f32 v208, v16, v211, v208
	v_fma_f32 v212, v17, v207, v212
	v_fma_f32 v231, v152, v232, v231
	v_fma_f32 v235, v152, v236, v235
	v_fma_f32 v231, v36, v236, v231
	v_fma_f32 v235, v37, v232, v235
	v_cvt_pk_bf16_f32 v132, v208, v212
	v_cvt_pk_bf16_f32 v143, v231, v235
	v_fma_f32 v209, v150, v208, v209
	v_fma_f32 v213, v150, v212, v213
	v_fma_f32 v209, v16, v212, v209
	v_fma_f32 v213, v17, v208, v213
	v_fma_f32 v230, v152, v231, v230
	v_fma_f32 v234, v152, v235, v234
	v_fma_f32 v230, v36, v235, v230
	v_fma_f32 v234, v37, v231, v234
	v_cvt_pk_bf16_f32 v135, v209, v213
	v_cvt_pk_bf16_f32 v187, v230, v234
	ds_write2_b32 v193, v132, v135 offset0:136 offset1:204
	ds_write2_b32 v254, v187, v143 offset0:0 offset1:68
	v_fma_f32 v214, v150, v209, v214
	v_fma_f32 v218, v150, v213, v218
	v_fma_f32 v214, v16, v213, v214
	v_fma_f32 v218, v17, v209, v218
	v_fma_f32 v225, v152, v230, v225
	v_fma_f32 v229, v152, v234, v229
	v_fma_f32 v225, v36, v234, v225
	v_fma_f32 v229, v37, v230, v229
	v_cvt_pk_bf16_f32 v128, v214, v218
	v_cvt_pk_bf16_f32 v136, v225, v229
	v_add_u32_e32 v193, 0x34c0, v103
	v_add_u32_e32 v254, 0x3900, v103
	v_fma_f32 v215, v150, v214, v215
	v_fma_f32 v219, v150, v218, v219
	v_fma_f32 v215, v16, v218, v215
	v_fma_f32 v219, v17, v214, v219
	v_fma_f32 v224, v152, v225, v224
	v_fma_f32 v228, v152, v229, v228
	v_fma_f32 v224, v36, v229, v224
	v_fma_f32 v228, v37, v225, v228
	v_cvt_pk_bf16_f32 v131, v215, v219
	v_cvt_pk_bf16_f32 v139, v224, v228
	ds_write2_b32 v193, v128, v131 offset0:0 offset1:68
	ds_write2_b32 v254, v139, v136 offset0:136 offset1:204
	v_fma_f32 v216, v150, v215, v216
	v_fma_f32 v220, v150, v219, v220
	v_fma_f32 v216, v16, v219, v216
	v_fma_f32 v220, v17, v215, v220
	v_fma_f32 v223, v152, v224, v223
	v_fma_f32 v227, v152, v228, v227
	v_fma_f32 v223, v36, v228, v223
	v_fma_f32 v227, v37, v224, v227
	v_cvt_pk_bf16_f32 v132, v216, v220
	v_cvt_pk_bf16_f32 v143, v223, v227
	v_fma_f32 v217, v150, v216, v217
	v_fma_f32 v221, v150, v220, v221
	v_fma_f32 v217, v16, v220, v217
	v_fma_f32 v221, v17, v216, v221
	v_fma_f32 v222, v152, v223, v222
	v_fma_f32 v226, v152, v227, v226
	v_fma_f32 v222, v36, v227, v222
	v_fma_f32 v226, v37, v223, v226
	v_cvt_pk_bf16_f32 v135, v217, v221
	v_cvt_pk_bf16_f32 v187, v222, v226
	ds_write2_b32 v193, v132, v135 offset0:136 offset1:204
	ds_write2_b32 v254, v187, v143 offset0:0 offset1:68
	v_mov_b32_e32 v114, v217
	v_mov_b32_e32 v119, v221
	v_mov_b32_e32 v121, v222
	v_mov_b32_e32 v127, v226
	ds_read_b128 v[188:191], v110 offset:10240
	ds_read_b128 v[194:197], v110 offset:10304
	ds_read_b128 v[198:201], v110 offset:10368
	ds_read_b128 v[202:205], v110 offset:10432
	ds_read_b128 v[206:209], v110 offset:14592
	ds_read_b128 v[210:213], v110 offset:14656
	ds_read_b128 v[214:217], v110 offset:14720
	ds_read_b128 v[218:221], v110 offset:14784
	s_waitcnt lgkmcnt(7)
	v_mfma_f32_16x16x32_bf16 v[44:47], v[0:3], v[188:191], v[44:47]
	s_waitcnt lgkmcnt(3)
	v_mfma_f32_16x16x32_bf16 v[48:51], v[20:23], v[206:209], v[48:51]
	v_mfma_f32_16x16x32_bf16 v[44:47], v[4:7], v[194:197], v[44:47]
	s_waitcnt lgkmcnt(2)
; __device__ __forceinline__ unsigned pk2(float lo, float hi) { f32x2 v = {lo, hi}; nbf2 r = __builtin_convertvector(v, nbf2); return __builtin_bit_cast(unsigned, r); }
; __device__ __forceinline__ float bf_lo(unsigned w) { return __uint_as_float(w << 16); }
; __device__ __forceinline__ float bf_hi(unsigned w) { return __uint_as_float(w & 0xffff0000u); }
; __device__ __forceinline__ float fast_rcp(float x) { return __builtin_amdgcn_rcpf(x); }
; __device__ __forceinline__ float fast_exp2(float x) { return __builtin_amdgcn_exp2f(x); }
; __device__ __forceinline__ float gelu_f(float v) {
;     const float av = fabsf(v), d = av * 0.2316418882f + 1.0f;
;     const float t = fast_rcp(d);
;     float q = t * 0.5307027145f + (-0.7265760135f); q = q * t + 0.7107068705f; q = q * t + (-0.142248368f); q = q * t + 0.127414796f; q = q * t;
;     const float e = fast_exp2((v * v) * (-0.72134752044f));
;     const float m = v * (q * e), r = v - m;
;     return v < 0.f ? m : r;
; }
; __device__ __forceinline__ void s5_out_phase(LAS unsigned char* lds, const bf16_t* UZ, const unsigned char* ws, const float* dskip, bf16_t* YG) {
;     ...
; #pragma unroll
;         for (int m = 0; m < 4; ++m) {
;             const unsigned u0 = (unsigned)(unsigned short)Uf[m][0] | ((unsigned)(unsigned short)Uf[m][1] << 16), u1 = (unsigned)(unsigned short)Uf[m][2] | ((unsigned)(unsigned short)Uf[m][3] << 16);
;             const float y0 = gelu_f(accY[m][0] + dsk[0] * bf_lo(u0)), y1 = gelu_f(accY[m][1] + dsk[1] * bf_hi(u0));
;             const float y2 = gelu_f(accY[m][2] + dsk[2] * bf_lo(u1)), y3 = gelu_f(accY[m][3] + dsk[3] * bf_hi(u1));
;             u32x2 w; w.x = pk2(y0, y1); w.y = pk2(y2, y3);
;             *(u32x2*)(YG + (size_t)(rowbase + 16 * m + fr) * D + 16 * g + 4 * fq) = w;
;         }
	v_mfma_f32_16x16x32_bf16 v[48:51], v[24:27], v[210:213], v[48:51]
	v_mfma_f32_16x16x32_bf16 v[44:47], v[8:11], v[198:201], v[44:47]
	s_waitcnt lgkmcnt(1)
	v_mfma_f32_16x16x32_bf16 v[48:51], v[28:31], v[214:217], v[48:51]
	v_mfma_f32_16x16x32_bf16 v[44:47], v[12:15], v[202:205], v[44:47]
	s_waitcnt lgkmcnt(0)
	v_mfma_f32_16x16x32_bf16 v[48:51], v[32:35], v[218:221], v[48:51]
	v_ashrrev_i32_e32 v167, 31, v166
	s_nop 7
	s_nop 4
	v_lshlrev_b32_e32 v188, 16, v172
	v_and_b32_e32 v189, 0xffff0000, v172
	s_waitcnt vmcnt(0)
	v_pk_fma_f32 v[188:189], v[40:41], v[188:189], v[48:49]
	v_lshlrev_b32_e32 v172, 16, v173
	v_fma_f32 v48, |v188|, s21, 1.0
	v_rcp_f32_e32 v190, v48
	v_fma_f32 v48, |v189|, s21, 1.0
	v_rcp_f32_e32 v191, v48
	v_pk_mul_f32 v[194:195], v[188:189], v[188:189]
	v_and_b32_e32 v173, 0xffff0000, v173
	v_mul_f32_e32 v48, 0xbf38aa3b, v194
	v_exp_f32_e32 v194, v48
	v_mov_b64_e32 v[48:49], s[4:5]
	v_pk_fma_f32 v[196:197], v[190:191], s[2:3], v[48:49] op_sel_hi:[1,0,0]
	v_mul_f32_e32 v114, 0xbf38aa3b, v195
	v_pk_fma_f32 v[196:197], v[190:191], v[196:197], s[8:9] op_sel_hi:[1,1,0]
	v_exp_f32_e32 v195, v114
	v_pk_fma_f32 v[196:197], v[190:191], v[196:197], s[20:21] op_sel_hi:[1,1,0]
	v_pk_fma_f32 v[50:51], v[42:43], v[172:173], v[50:51]
	v_pk_fma_f32 v[196:197], v[190:191], v[196:197], s[22:23] op_sel_hi:[1,1,0]
	v_fma_f32 v121, |v50|, s21, 1.0
	v_pk_mul_f32 v[190:191], v[190:191], v[196:197]
	v_rcp_f32_e32 v172, v121
	v_fma_f32 v121, |v51|, s21, 1.0
	v_pk_mul_f32 v[190:191], v[194:195], v[190:191]
	v_rcp_f32_e32 v173, v121
	v_pk_mul_f32 v[194:195], v[188:189], v[190:191]
	v_pk_fma_f32 v[190:191], v[188:189], v[190:191], v[188:189] neg_lo:[1,0,0] neg_hi:[1,0,0]
	v_cmp_gt_f32_e32 vcc, 0, v189
	s_nop 1
	v_cndmask_b32_e32 v114, v191, v195, vcc
	v_cmp_gt_f32_e32 vcc, 0, v188
	v_pk_mul_f32 v[188:189], v[50:51], v[50:51]
	s_nop 0
	v_mul_f32_e32 v121, 0xbf38aa3b, v188
	v_cndmask_b32_e32 v119, v190, v194, vcc
	v_exp_f32_e32 v188, v121
	v_pk_fma_f32 v[190:191], v[172:173], s[2:3], v[48:49] op_sel_hi:[1,0,0]
	v_mul_f32_e32 v121, 0xbf38aa3b, v189
	v_pk_fma_f32 v[190:191], v[172:173], v[190:191], s[8:9] op_sel_hi:[1,1,0]
	v_exp_f32_e32 v189, v121
	v_pk_fma_f32 v[190:191], v[172:173], v[190:191], s[20:21] op_sel_hi:[1,1,0]
	v_cmp_gt_f32_e32 vcc, 0, v51
	v_pk_fma_f32 v[190:191], v[172:173], v[190:191], s[22:23] op_sel_hi:[1,1,0]
	s_nop 0
	v_pk_mul_f32 v[172:173], v[172:173], v[190:191]
	s_nop 0
	v_pk_mul_f32 v[172:173], v[188:189], v[172:173]
	s_nop 0
	v_pk_mul_f32 v[188:189], v[50:51], v[172:173]
	v_pk_fma_f32 v[172:173], v[50:51], v[172:173], v[50:51] neg_lo:[1,0,0] neg_hi:[1,0,0]
	s_nop 0
	v_cndmask_b32_e32 v51, v173, v189, vcc
	v_cmp_gt_f32_e32 vcc, 0, v50
	v_cvt_pk_bf16_f32 v50, v119, v114
	s_nop 0
	v_cndmask_b32_e32 v121, v172, v188, vcc
	v_lshlrev_b64 v[172:173], 11, v[166:167]
	v_cvt_pk_bf16_f32 v51, v121, v51
	v_lshl_add_u64 v[172:173], v[154:155], 0, v[172:173]
	global_store_dwordx2 v[172:173], v[50:51], off
	v_lshlrev_b32_e32 v50, 16, v170
	v_and_b32_e32 v51, 0xffff0000, v170
	v_pk_fma_f32 v[50:51], v[40:41], v[50:51], v[56:57]
	s_nop 0
	v_fma_f32 v56, |v50|, s21, 1.0
	v_fma_f32 v57, |v51|, s21, 1.0
	v_rcp_f32_e32 v56, v56
	v_rcp_f32_e32 v57, v57
	v_pk_mul_f32 v[172:173], v[50:51], v[50:51]
	v_cmp_gt_f32_e32 vcc, 0, v51
	v_mul_f32_e32 v114, 0xbf38aa3b, v172
	v_exp_f32_e32 v172, v114
	v_pk_fma_f32 v[188:189], v[56:57], s[2:3], v[48:49] op_sel_hi:[1,0,0]
	v_mul_f32_e32 v114, 0xbf38aa3b, v173
	v_pk_fma_f32 v[188:189], v[56:57], v[188:189], s[8:9] op_sel_hi:[1,1,0]
	v_exp_f32_e32 v173, v114
	v_pk_fma_f32 v[188:189], v[56:57], v[188:189], s[20:21] op_sel_hi:[1,1,0]
	s_nop 0
	v_pk_fma_f32 v[188:189], v[56:57], v[188:189], s[22:23] op_sel_hi:[1,1,0]
	s_nop 0
	v_pk_mul_f32 v[56:57], v[56:57], v[188:189]
	s_nop 0
	v_pk_mul_f32 v[56:57], v[172:173], v[56:57]
	s_nop 0
	v_pk_mul_f32 v[172:173], v[50:51], v[56:57]
	v_pk_fma_f32 v[56:57], v[50:51], v[56:57], v[50:51] neg_lo:[1,0,0] neg_hi:[1,0,0]
	v_and_b32_e32 v51, 0xffff0000, v171
	v_cndmask_b32_e32 v114, v57, v173, vcc
	v_cmp_gt_f32_e32 vcc, 0, v50
	v_lshlrev_b32_e32 v50, 16, v171
	v_pk_fma_f32 v[50:51], v[42:43], v[50:51], v[58:59]
	v_cndmask_b32_e32 v119, v56, v172, vcc
	v_fma_f32 v56, |v50|, s21, 1.0
	v_fma_f32 v57, |v51|, s21, 1.0
	v_rcp_f32_e32 v56, v56
	v_rcp_f32_e32 v57, v57
	v_pk_mul_f32 v[58:59], v[50:51], v[50:51]
	v_cmp_gt_f32_e32 vcc, 0, v51
	v_mul_f32_e32 v58, 0xbf38aa3b, v58
	v_pk_fma_f32 v[170:171], v[56:57], s[2:3], v[48:49] op_sel_hi:[1,0,0]
	v_mul_f32_e32 v59, 0xbf38aa3b, v59
	v_exp_f32_e32 v58, v58
	v_pk_fma_f32 v[170:171], v[56:57], v[170:171], s[8:9] op_sel_hi:[1,1,0]
	v_exp_f32_e32 v59, v59
	v_pk_fma_f32 v[170:171], v[56:57], v[170:171], s[20:21] op_sel_hi:[1,1,0]
	v_mov_b64_e32 v[172:173], v[174:175]
	v_pk_fma_f32 v[170:171], v[56:57], v[170:171], s[22:23] op_sel_hi:[1,1,0]
	s_nop 0
	v_pk_mul_f32 v[56:57], v[56:57], v[170:171]
	v_mov_b64_e32 v[170:171], v[176:177]
	v_pk_mul_f32 v[56:57], v[58:59], v[56:57]
	s_nop 0
	v_pk_mul_f32 v[58:59], v[50:51], v[56:57]
	v_pk_fma_f32 v[56:57], v[50:51], v[56:57], v[50:51] neg_lo:[1,0,0] neg_hi:[1,0,0]
	s_nop 0
	v_cndmask_b32_e32 v51, v57, v59, vcc
	v_cmp_gt_f32_e32 vcc, 0, v50
	v_cvt_pk_bf16_f32 v50, v119, v114
	s_nop 0
; __device__ __forceinline__ unsigned pk2(float lo, float hi) { f32x2 v = {lo, hi}; nbf2 r = __builtin_convertvector(v, nbf2); return __builtin_bit_cast(unsigned, r); }
; __device__ __forceinline__ float bf_lo(unsigned w) { return __uint_as_float(w << 16); }
; __device__ __forceinline__ float bf_hi(unsigned w) { return __uint_as_float(w & 0xffff0000u); }
; __device__ __forceinline__ float fast_rcp(float x) { return __builtin_amdgcn_rcpf(x); }
; __device__ __forceinline__ float fast_exp2(float x) { return __builtin_amdgcn_exp2f(x); }
; __device__ __forceinline__ float gelu_f(float v) {
;     const float av = fabsf(v), d = av * 0.2316418882f + 1.0f;
;     const float t = fast_rcp(d);
;     float q = t * 0.5307027145f + (-0.7265760135f); q = q * t + 0.7107068705f; q = q * t + (-0.142248368f); q = q * t + 0.127414796f; q = q * t;
;     const float e = fast_exp2((v * v) * (-0.72134752044f));
;     const float m = v * (q * e), r = v - m;
;     return v < 0.f ? m : r;
; }
; __device__ __forceinline__ void s5_out_phase(LAS unsigned char* lds, const bf16_t* UZ, const unsigned char* ws, const float* dskip, bf16_t* YG) {
;     ...
; #pragma unroll
;         for (int m = 0; m < 4; ++m) {
;             const unsigned u0 = (unsigned)(unsigned short)Uf[m][0] | ((unsigned)(unsigned short)Uf[m][1] << 16), u1 = (unsigned)(unsigned short)Uf[m][2] | ((unsigned)(unsigned short)Uf[m][3] << 16);
;             const float y0 = gelu_f(accY[m][0] + dsk[0] * bf_lo(u0)), y1 = gelu_f(accY[m][1] + dsk[1] * bf_hi(u0));
;             const float y2 = gelu_f(accY[m][2] + dsk[2] * bf_lo(u1)), y3 = gelu_f(accY[m][3] + dsk[3] * bf_hi(u1));
;             u32x2 w; w.x = pk2(y0, y1); w.y = pk2(y2, y3);
;             *(u32x2*)(YG + (size_t)(rowbase + 16 * m + fr) * D + 16 * g + 4 * fq) = w;
;         }
	v_cndmask_b32_e32 v56, v56, v58, vcc
	v_cvt_pk_bf16_f32 v51, v56, v51
	v_add_u32_e32 v56, 16, v166
	v_ashrrev_i32_e32 v57, 31, v56
	v_lshlrev_b64 v[56:57], 11, v[56:57]
	v_lshl_add_u64 v[56:57], v[154:155], 0, v[56:57]
	global_store_dwordx2 v[56:57], v[50:51], off
	v_lshlrev_b32_e32 v50, 16, v168
	v_and_b32_e32 v51, 0xffff0000, v168
	v_pk_fma_f32 v[50:51], v[40:41], v[50:51], v[52:53]
	s_nop 0
	v_fma_f32 v52, |v50|, s21, 1.0
	v_fma_f32 v53, |v51|, s21, 1.0
	v_rcp_f32_e32 v52, v52
	v_rcp_f32_e32 v53, v53
	v_pk_mul_f32 v[56:57], v[50:51], v[50:51]
	v_cmp_gt_f32_e32 vcc, 0, v51
	v_mul_f32_e32 v56, 0xbf38aa3b, v56
	v_pk_fma_f32 v[58:59], v[52:53], s[2:3], v[48:49] op_sel_hi:[1,0,0]
	v_mul_f32_e32 v57, 0xbf38aa3b, v57
	v_exp_f32_e32 v56, v56
	v_pk_fma_f32 v[58:59], v[52:53], v[58:59], s[8:9] op_sel_hi:[1,1,0]
	v_exp_f32_e32 v57, v57
	v_pk_fma_f32 v[58:59], v[52:53], v[58:59], s[20:21] op_sel_hi:[1,1,0]
	s_nop 0
	v_pk_fma_f32 v[58:59], v[52:53], v[58:59], s[22:23] op_sel_hi:[1,1,0]
	s_nop 0
	v_pk_mul_f32 v[52:53], v[52:53], v[58:59]
	s_nop 0
	v_pk_mul_f32 v[52:53], v[56:57], v[52:53]
	s_nop 0
	v_pk_mul_f32 v[56:57], v[50:51], v[52:53]
	v_pk_fma_f32 v[52:53], v[50:51], v[52:53], v[50:51] neg_lo:[1,0,0] neg_hi:[1,0,0]
	v_and_b32_e32 v51, 0xffff0000, v169
	v_cndmask_b32_e32 v58, v53, v57, vcc
	v_cmp_gt_f32_e32 vcc, 0, v50
	v_lshlrev_b32_e32 v50, 16, v169
	v_pk_fma_f32 v[50:51], v[42:43], v[50:51], v[54:55]
	v_cndmask_b32_e32 v59, v52, v56, vcc
	v_fma_f32 v52, |v50|, s21, 1.0
	v_fma_f32 v53, |v51|, s21, 1.0
	v_rcp_f32_e32 v52, v52
	v_rcp_f32_e32 v53, v53
	v_pk_mul_f32 v[54:55], v[50:51], v[50:51]
	v_cmp_gt_f32_e32 vcc, 0, v51
	v_mul_f32_e32 v54, 0xbf38aa3b, v54
	v_pk_fma_f32 v[56:57], v[52:53], s[2:3], v[48:49] op_sel_hi:[1,0,0]
	v_mul_f32_e32 v55, 0xbf38aa3b, v55
	v_exp_f32_e32 v54, v54
	v_pk_fma_f32 v[56:57], v[52:53], v[56:57], s[8:9] op_sel_hi:[1,1,0]
	v_exp_f32_e32 v55, v55
	v_pk_fma_f32 v[56:57], v[52:53], v[56:57], s[20:21] op_sel_hi:[1,1,0]
	v_mov_b64_e32 v[168:169], v[178:179]
	v_pk_fma_f32 v[56:57], v[52:53], v[56:57], s[22:23] op_sel_hi:[1,1,0]
	s_nop 0
	v_pk_mul_f32 v[52:53], v[52:53], v[56:57]
	s_nop 0
	v_pk_mul_f32 v[52:53], v[54:55], v[52:53]
	s_nop 0
	v_pk_mul_f32 v[54:55], v[50:51], v[52:53]
	v_pk_fma_f32 v[52:53], v[50:51], v[52:53], v[50:51] neg_lo:[1,0,0] neg_hi:[1,0,0]
	s_nop 0
	v_cndmask_b32_e32 v51, v53, v55, vcc
	v_cmp_gt_f32_e32 vcc, 0, v50
	v_cvt_pk_bf16_f32 v50, v59, v58
	s_nop 0
	v_cndmask_b32_e32 v52, v52, v54, vcc
	v_cvt_pk_bf16_f32 v51, v52, v51
	v_add_u32_e32 v52, 32, v166
	v_ashrrev_i32_e32 v53, 31, v52
	v_lshlrev_b64 v[52:53], 11, v[52:53]
	v_lshl_add_u64 v[52:53], v[154:155], 0, v[52:53]
	global_store_dwordx2 v[52:53], v[50:51], off
	v_lshlrev_b32_e32 v50, 16, v116
	v_and_b32_e32 v51, 0xffff0000, v116
	v_pk_fma_f32 v[44:45], v[40:41], v[50:51], v[44:45]
	s_nop 0
	v_fma_f32 v50, |v44|, s21, 1.0
	v_fma_f32 v51, |v45|, s21, 1.0
	v_rcp_f32_e32 v50, v50
	v_rcp_f32_e32 v51, v51
	v_pk_mul_f32 v[52:53], v[44:45], v[44:45]
	v_cmp_gt_f32_e32 vcc, 0, v45
	v_mul_f32_e32 v52, 0xbf38aa3b, v52
	v_pk_fma_f32 v[54:55], v[50:51], s[2:3], v[48:49] op_sel_hi:[1,0,0]
	v_mul_f32_e32 v53, 0xbf38aa3b, v53
	v_exp_f32_e32 v52, v52
	v_pk_fma_f32 v[54:55], v[50:51], v[54:55], s[8:9] op_sel_hi:[1,1,0]
	v_exp_f32_e32 v53, v53
	v_pk_fma_f32 v[54:55], v[50:51], v[54:55], s[20:21] op_sel_hi:[1,1,0]
	s_nop 0
	v_pk_fma_f32 v[54:55], v[50:51], v[54:55], s[22:23] op_sel_hi:[1,1,0]
	s_nop 0
	v_pk_mul_f32 v[50:51], v[50:51], v[54:55]
	s_nop 0
	v_pk_mul_f32 v[50:51], v[52:53], v[50:51]
	s_nop 0
	v_pk_mul_f32 v[52:53], v[44:45], v[50:51]
	v_pk_fma_f32 v[50:51], v[44:45], v[50:51], v[44:45] neg_lo:[1,0,0] neg_hi:[1,0,0]
	v_and_b32_e32 v45, 0xffff0000, v117
	v_cndmask_b32_e32 v53, v51, v53, vcc
	v_cmp_gt_f32_e32 vcc, 0, v44
	v_lshlrev_b32_e32 v44, 16, v117
	v_pk_fma_f32 v[44:45], v[42:43], v[44:45], v[46:47]
	v_cndmask_b32_e32 v52, v50, v52, vcc
	v_fma_f32 v46, |v44|, s21, 1.0
	v_fma_f32 v47, |v45|, s21, 1.0
	v_rcp_f32_e32 v46, v46
	v_rcp_f32_e32 v47, v47
	v_pk_mul_f32 v[50:51], v[44:45], v[44:45]
	v_cmp_gt_f32_e32 vcc, 0, v45
	v_mul_f32_e32 v50, 0xbf38aa3b, v50
	v_pk_fma_f32 v[48:49], v[46:47], s[2:3], v[48:49] op_sel_hi:[1,0,0]
	v_mul_f32_e32 v51, 0xbf38aa3b, v51
	v_exp_f32_e32 v50, v50
	v_pk_fma_f32 v[48:49], v[46:47], v[48:49], s[8:9] op_sel_hi:[1,1,0]
	v_exp_f32_e32 v51, v51
	v_pk_fma_f32 v[48:49], v[46:47], v[48:49], s[20:21] op_sel_hi:[1,1,0]
	v_mov_b64_e32 v[116:117], v[180:181]
	v_pk_fma_f32 v[48:49], v[46:47], v[48:49], s[22:23] op_sel_hi:[1,1,0]
	s_nop 0
	v_pk_mul_f32 v[46:47], v[46:47], v[48:49]
	s_nop 0
	v_pk_mul_f32 v[46:47], v[50:51], v[46:47]
	s_nop 0
	v_pk_mul_f32 v[48:49], v[44:45], v[46:47]
	v_pk_fma_f32 v[46:47], v[44:45], v[46:47], v[44:45] neg_lo:[1,0,0] neg_hi:[1,0,0]
	s_nop 0
	v_cndmask_b32_e32 v45, v47, v49, vcc
	v_cmp_gt_f32_e32 vcc, 0, v44
	v_cvt_pk_bf16_f32 v44, v52, v53
	s_nop 0
	v_cndmask_b32_e32 v46, v46, v48, vcc
	v_cvt_pk_bf16_f32 v45, v46, v45
	v_add_u32_e32 v46, 48, v166
	v_ashrrev_i32_e32 v47, 31, v46
	v_lshlrev_b64 v[46:47], 11, v[46:47]
	v_lshl_add_u64 v[46:47], v[154:155], 0, v[46:47]
	v_add_u32_e32 v166, s3, v166
	s_andn2_b64 vcc, exec, s[24:25]
	global_store_dwordx2 v[46:47], v[44:45], off
	s_cbranch_vccz .LBB0_762
